# cache policy: final-rmsnorm Y loads use the default policy instead of nt
# speedup vs baseline: 1.0003x; 1.0003x over previous
; #define ws (karg_ws())
; __global__ void __launch_bounds__(512, 2) fwd_megakernel(Args a) {
;     ...
;     for (int r = gw; r < MT; r += NGW) {
;         f32x4* yr = (f32x4*)(Y + (size_t)r * DM) + lane;
;         f32x4 v[4]; float s = 0.f;
;         if (r < MP) {
; #pragma unroll
;             for (int j = 0; j < 4; ++j) v[j] = __builtin_nontemporal_load(&yr[64 * j]);
;         } else {
; #pragma unroll
;             for (int j = 0; j < 4; ++j) { const u32x2 w = ((const u32x2*)(X1B + (size_t)r * DM))[lane + 64 * j]; v[j] = (f32x4){bflo(w.x), bfhi(w.x), bflo(w.y), bfhi(w.y)}; }
;         }
;         if (r >= MP) {
;             for (int ks = 0; ks < 11; ++ks) { const f32x4* pr = (const f32x4*)((float*)(ws + WS_PART) + ((size_t)ks * MS + (r - MP)) * DM) + lane;
; #pragma unroll
;                 for (int j = 0; j < 4; ++j) v[j] = v[j] + pr[64 * j]; } }
.Lp9_fast:
	s_load_dwordx4 s[4:7], s[92:93], 0xd8
	s_load_dwordx2 s[2:3], s[92:93], 0xe8
	v_and_b32_e32 v2, 63, v228
	v_lshlrev_b32_e32 v3, 4, v2
	v_lshlrev_b32_e32 v1, 3, v2
	s_lshl_b32 s9, s8, 12
	s_lshl_b32 s14, s8, 11
	v_add_u32_e32 v0, s9, v3
	v_add_u32_e32 v1, s14, v1
	v_mov_b32_e32 v20, 0x358637bd
	v_mov_b32_e32 v21, 0x260
	s_mov_b32 s19, 0xf800000
	s_waitcnt lgkmcnt(0)
	s_add_u32 s10, s2, 0x19800000
	s_addc_u32 s11, s3, 0
	s_add_u32 s12, s2, 0xec00000
	s_addc_u32 s13, s3, 0
	global_load_dwordx4 v[96:99], v3, s[4:5] offset:0
	global_load_dwordx4 v[100:103], v3, s[4:5] offset:1024
	global_load_dwordx4 v[104:107], v3, s[4:5] offset:2048
	global_load_dwordx4 v[108:111], v3, s[4:5] offset:3072
	v_add_u32_e32 v12, 0x7800000, v0
	global_load_dwordx4 v[32:35], v12, s[6:7] offset:0
	global_load_dwordx4 v[36:39], v12, s[6:7] offset:1024
	global_load_dwordx4 v[40:43], v12, s[6:7] offset:2048
	global_load_dwordx4 v[44:47], v12, s[6:7] offset:3072
	v_add_u32_e32 v13, 0x7000000, v0
	global_load_dwordx4 v[48:51], v13, s[6:7] offset:0
	global_load_dwordx4 v[52:55], v13, s[6:7] offset:1024
	global_load_dwordx4 v[56:59], v13, s[6:7] offset:2048
	global_load_dwordx4 v[60:63], v13, s[6:7] offset:3072
	v_add_u32_e32 v14, 0x6800000, v0
	global_load_dwordx4 v[64:67], v14, s[6:7] offset:0
	global_load_dwordx4 v[68:71], v14, s[6:7] offset:1024
	global_load_dwordx4 v[72:75], v14, s[6:7] offset:2048
	global_load_dwordx4 v[76:79], v14, s[6:7] offset:3072
	v_add_u32_e32 v15, 0x6000000, v0
	global_load_dwordx4 v[80:83], v15, s[6:7] offset:0
	global_load_dwordx4 v[84:87], v15, s[6:7] offset:1024
	global_load_dwordx4 v[88:91], v15, s[6:7] offset:2048
	global_load_dwordx4 v[92:95], v15, s[6:7] offset:3072
	s_cmpk_lt_i32 s8, 0x200
	s_cbranch_scc0 .Lp9_prompt
	global_load_dwordx2 v[112:113], v1, s[10:11] offset:0
	global_load_dwordx2 v[114:115], v1, s[10:11] offset:512
	global_load_dwordx2 v[116:117], v1, s[10:11] offset:1024
	global_load_dwordx2 v[118:119], v1, s[10:11] offset:1536
	global_load_dwordx4 v[120:123], v0, s[12:13] offset:0
	global_load_dwordx4 v[124:127], v0, s[12:13] offset:1024
	global_load_dwordx4 v[128:131], v0, s[12:13] offset:2048
	global_load_dwordx4 v[132:135], v0, s[12:13] offset:3072
	v_add_u32_e32 v7, 0x200000, v0
	global_load_dwordx4 v[136:139], v7, s[12:13] offset:0
	global_load_dwordx4 v[140:143], v7, s[12:13] offset:1024
	global_load_dwordx4 v[144:147], v7, s[12:13] offset:2048
	global_load_dwordx4 v[148:151], v7, s[12:13] offset:3072
	v_add_u32_e32 v8, 0x400000, v0
	global_load_dwordx4 v[152:155], v8, s[12:13] offset:0
	global_load_dwordx4 v[156:159], v8, s[12:13] offset:1024
	global_load_dwordx4 v[160:163], v8, s[12:13] offset:2048
	global_load_dwordx4 v[164:167], v8, s[12:13] offset:3072
	v_add_u32_e32 v9, 0x600000, v0
	global_load_dwordx4 v[168:171], v9, s[12:13] offset:0
	global_load_dwordx4 v[172:175], v9, s[12:13] offset:1024
	global_load_dwordx4 v[176:179], v9, s[12:13] offset:2048
	global_load_dwordx4 v[180:183], v9, s[12:13] offset:3072
	v_add_u32_e32 v10, 0x800000, v0
	global_load_dwordx4 v[184:187], v10, s[12:13] offset:0
	global_load_dwordx4 v[188:191], v10, s[12:13] offset:1024
	global_load_dwordx4 v[192:195], v10, s[12:13] offset:2048
	global_load_dwordx4 v[196:199], v10, s[12:13] offset:3072
	v_add_u32_e32 v11, 0xa00000, v0
	global_load_dwordx4 v[200:203], v11, s[12:13] offset:0
	global_load_dwordx4 v[204:207], v11, s[12:13] offset:1024
	global_load_dwordx4 v[208:211], v11, s[12:13] offset:2048
	global_load_dwordx4 v[212:215], v11, s[12:13] offset:3072
	s_waitcnt vmcnt(0)
	v_lshlrev_b32_e32 v216, 16, v112
	v_and_b32_e32 v217, 0xffff0000, v112
	v_lshlrev_b32_e32 v218, 16, v113
	v_and_b32_e32 v219, 0xffff0000, v113
	v_lshlrev_b32_e32 v220, 16, v114
	v_and_b32_e32 v221, 0xffff0000, v114
	v_lshlrev_b32_e32 v222, 16, v115
	v_and_b32_e32 v223, 0xffff0000, v115
	v_lshlrev_b32_e32 v224, 16, v116
	v_and_b32_e32 v225, 0xffff0000, v116
	v_lshlrev_b32_e32 v226, 16, v117
	v_and_b32_e32 v227, 0xffff0000, v117
	v_lshlrev_b32_e32 v228, 16, v118
	v_and_b32_e32 v229, 0xffff0000, v118
	v_lshlrev_b32_e32 v230, 16, v119
	v_and_b32_e32 v231, 0xffff0000, v119
	v_pk_add_f32 v[216:217], v[216:217], v[120:121]
	v_pk_add_f32 v[218:219], v[218:219], v[122:123]
	v_pk_add_f32 v[220:221], v[220:221], v[124:125]
	v_pk_add_f32 v[222:223], v[222:223], v[126:127]
	v_pk_add_f32 v[224:225], v[224:225], v[128:129]
	v_pk_add_f32 v[226:227], v[226:227], v[130:131]
	v_pk_add_f32 v[228:229], v[228:229], v[132:133]
	v_pk_add_f32 v[230:231], v[230:231], v[134:135]
	v_pk_add_f32 v[216:217], v[216:217], v[136:137]
	v_pk_add_f32 v[218:219], v[218:219], v[138:139]
	v_pk_add_f32 v[220:221], v[220:221], v[140:141]
	v_pk_add_f32 v[222:223], v[222:223], v[142:143]
	v_pk_add_f32 v[224:225], v[224:225], v[144:145]
	v_pk_add_f32 v[226:227], v[226:227], v[146:147]
	v_pk_add_f32 v[228:229], v[228:229], v[148:149]
	v_pk_add_f32 v[230:231], v[230:231], v[150:151]
	v_pk_add_f32 v[216:217], v[216:217], v[152:153]
	v_pk_add_f32 v[218:219], v[218:219], v[154:155]
	v_pk_add_f32 v[220:221], v[220:221], v[156:157]
	v_pk_add_f32 v[222:223], v[222:223], v[158:159]
	v_pk_add_f32 v[224:225], v[224:225], v[160:161]
	v_pk_add_f32 v[226:227], v[226:227], v[162:163]
	v_pk_add_f32 v[228:229], v[228:229], v[164:165]
	v_pk_add_f32 v[230:231], v[230:231], v[166:167]
	v_pk_add_f32 v[216:217], v[216:217], v[168:169]
	v_pk_add_f32 v[218:219], v[218:219], v[170:171]
	v_pk_add_f32 v[220:221], v[220:221], v[172:173]
	v_pk_add_f32 v[222:223], v[222:223], v[174:175]
	v_pk_add_f32 v[224:225], v[224:225], v[176:177]
	v_pk_add_f32 v[226:227], v[226:227], v[178:179]
	v_pk_add_f32 v[228:229], v[228:229], v[180:181]
; #define ws (karg_ws())
; __global__ void __launch_bounds__(512, 2) fwd_megakernel(Args a) {
;     ...
;         if (r >= MP) {
;             for (int ks = 0; ks < 11; ++ks) { const f32x4* pr = (const f32x4*)((float*)(ws + WS_PART) + ((size_t)ks * MS + (r - MP)) * DM) + lane;
; #pragma unroll
;                 for (int j = 0; j < 4; ++j) v[j] = v[j] + pr[64 * j]; } }
; #pragma unroll
;         for (int j = 0; j < 4; ++j) s += (v[j][0] * v[j][0] + v[j][1] * v[j][1]) + (v[j][2] * v[j][2] + v[j][3] * v[j][3]);
;         const float rs = 1.0f / sqrtf(wave_sum(s) * (1.0f / DM) + EPS);
	v_pk_add_f32 v[230:231], v[230:231], v[182:183]
	v_pk_add_f32 v[216:217], v[216:217], v[184:185]
	v_pk_add_f32 v[218:219], v[218:219], v[186:187]
	v_pk_add_f32 v[220:221], v[220:221], v[188:189]
	v_pk_add_f32 v[222:223], v[222:223], v[190:191]
	v_pk_add_f32 v[224:225], v[224:225], v[192:193]
	v_pk_add_f32 v[226:227], v[226:227], v[194:195]
	v_pk_add_f32 v[228:229], v[228:229], v[196:197]
	v_pk_add_f32 v[230:231], v[230:231], v[198:199]
	v_pk_add_f32 v[216:217], v[216:217], v[200:201]
	v_pk_add_f32 v[218:219], v[218:219], v[202:203]
	v_pk_add_f32 v[220:221], v[220:221], v[204:205]
	v_pk_add_f32 v[222:223], v[222:223], v[206:207]
	v_pk_add_f32 v[224:225], v[224:225], v[208:209]
	v_pk_add_f32 v[226:227], v[226:227], v[210:211]
	v_pk_add_f32 v[228:229], v[228:229], v[212:213]
	v_pk_add_f32 v[230:231], v[230:231], v[214:215]
	v_add_u32_e32 v6, 0xc00000, v0
	global_load_dwordx4 v[120:123], v6, s[12:13] offset:0
	global_load_dwordx4 v[124:127], v6, s[12:13] offset:1024
	global_load_dwordx4 v[128:131], v6, s[12:13] offset:2048
	global_load_dwordx4 v[132:135], v6, s[12:13] offset:3072
	v_add_u32_e32 v7, 0xe00000, v0
	global_load_dwordx4 v[136:139], v7, s[12:13] offset:0
	global_load_dwordx4 v[140:143], v7, s[12:13] offset:1024
	global_load_dwordx4 v[144:147], v7, s[12:13] offset:2048
	global_load_dwordx4 v[148:151], v7, s[12:13] offset:3072
	v_add_u32_e32 v8, 0x1000000, v0
	global_load_dwordx4 v[152:155], v8, s[12:13] offset:0
	global_load_dwordx4 v[156:159], v8, s[12:13] offset:1024
	global_load_dwordx4 v[160:163], v8, s[12:13] offset:2048
	global_load_dwordx4 v[164:167], v8, s[12:13] offset:3072
	v_add_u32_e32 v9, 0x1200000, v0
	global_load_dwordx4 v[168:171], v9, s[12:13] offset:0
	global_load_dwordx4 v[172:175], v9, s[12:13] offset:1024
	global_load_dwordx4 v[176:179], v9, s[12:13] offset:2048
	global_load_dwordx4 v[180:183], v9, s[12:13] offset:3072
	v_add_u32_e32 v10, 0x1400000, v0
	global_load_dwordx4 v[184:187], v10, s[12:13] offset:0
	global_load_dwordx4 v[188:191], v10, s[12:13] offset:1024
	global_load_dwordx4 v[192:195], v10, s[12:13] offset:2048
	global_load_dwordx4 v[196:199], v10, s[12:13] offset:3072
	s_waitcnt vmcnt(0)
	v_pk_add_f32 v[216:217], v[216:217], v[120:121]
	v_pk_add_f32 v[218:219], v[218:219], v[122:123]
	v_pk_add_f32 v[220:221], v[220:221], v[124:125]
	v_pk_add_f32 v[222:223], v[222:223], v[126:127]
	v_pk_add_f32 v[224:225], v[224:225], v[128:129]
	v_pk_add_f32 v[226:227], v[226:227], v[130:131]
	v_pk_add_f32 v[228:229], v[228:229], v[132:133]
	v_pk_add_f32 v[230:231], v[230:231], v[134:135]
	v_pk_add_f32 v[216:217], v[216:217], v[136:137]
	v_pk_add_f32 v[218:219], v[218:219], v[138:139]
	v_pk_add_f32 v[220:221], v[220:221], v[140:141]
	v_pk_add_f32 v[222:223], v[222:223], v[142:143]
	v_pk_add_f32 v[224:225], v[224:225], v[144:145]
	v_pk_add_f32 v[226:227], v[226:227], v[146:147]
	v_pk_add_f32 v[228:229], v[228:229], v[148:149]
	v_pk_add_f32 v[230:231], v[230:231], v[150:151]
	v_pk_add_f32 v[216:217], v[216:217], v[152:153]
	v_pk_add_f32 v[218:219], v[218:219], v[154:155]
	v_pk_add_f32 v[220:221], v[220:221], v[156:157]
	v_pk_add_f32 v[222:223], v[222:223], v[158:159]
	v_pk_add_f32 v[224:225], v[224:225], v[160:161]
	v_pk_add_f32 v[226:227], v[226:227], v[162:163]
	v_pk_add_f32 v[228:229], v[228:229], v[164:165]
	v_pk_add_f32 v[230:231], v[230:231], v[166:167]
	v_pk_add_f32 v[216:217], v[216:217], v[168:169]
	v_pk_add_f32 v[218:219], v[218:219], v[170:171]
	v_pk_add_f32 v[220:221], v[220:221], v[172:173]
	v_pk_add_f32 v[222:223], v[222:223], v[174:175]
	v_pk_add_f32 v[224:225], v[224:225], v[176:177]
	v_pk_add_f32 v[226:227], v[226:227], v[178:179]
	v_pk_add_f32 v[228:229], v[228:229], v[180:181]
	v_pk_add_f32 v[230:231], v[230:231], v[182:183]
	v_pk_add_f32 v[216:217], v[216:217], v[184:185]
	v_pk_add_f32 v[218:219], v[218:219], v[186:187]
	v_pk_add_f32 v[220:221], v[220:221], v[188:189]
	v_pk_add_f32 v[222:223], v[222:223], v[190:191]
	v_pk_add_f32 v[224:225], v[224:225], v[192:193]
	v_pk_add_f32 v[226:227], v[226:227], v[194:195]
	v_pk_add_f32 v[228:229], v[228:229], v[196:197]
	v_pk_add_f32 v[230:231], v[230:231], v[198:199]
	v_add_u32_e32 v10, 0x8000000, v0
	v_pk_mul_f32 v[2:3], v[216:217], v[216:217]
	v_pk_fma_f32 v[2:3], v[218:219], v[218:219], v[2:3]
	v_pk_fma_f32 v[2:3], v[220:221], v[220:221], v[2:3]
	v_pk_fma_f32 v[2:3], v[222:223], v[222:223], v[2:3]
	v_pk_fma_f32 v[2:3], v[224:225], v[224:225], v[2:3]
	v_pk_fma_f32 v[2:3], v[226:227], v[226:227], v[2:3]
	v_pk_fma_f32 v[2:3], v[228:229], v[228:229], v[2:3]
	v_pk_fma_f32 v[2:3], v[230:231], v[230:231], v[2:3]
	v_add_f32_e32 v2, v2, v3
	s_nop 1
	v_add_f32_dpp v2, v2, v2 quad_perm:[1,0,3,2] row_mask:0xf bank_mask:0xf
	s_nop 1
	v_add_f32_dpp v2, v2, v2 quad_perm:[2,3,0,1] row_mask:0xf bank_mask:0xf
	s_nop 1
	v_add_f32_dpp v2, v2, v2 row_half_mirror row_mask:0xf bank_mask:0xf
	s_nop 1
	v_add_f32_dpp v2, v2, v2 row_mirror row_mask:0xf bank_mask:0xf
	s_nop 1
	v_readlane_b32 s20, v2, 0
	v_readlane_b32 s21, v2, 16
	v_readlane_b32 s22, v2, 32
	v_readlane_b32 s23, v2, 48
	s_nop 1
	v_mov_b32_e32 v4, s20
	v_add_f32_e32 v4, s21, v4
	v_add_f32_e32 v4, s22, v4
	v_add_f32_e32 v4, s23, v4
	v_fmamk_f32 v4, v4, 0x3a800000, v20
	v_mul_f32_e32 v5, 0x4f800000, v4
	v_cmp_gt_f32_e32 vcc, s19, v4
	s_nop 1
	v_cndmask_b32_e32 v4, v4, v5, vcc
	v_sqrt_f32_e32 v5, v4
	s_nop 0
	v_add_u32_e32 v6, -1, v5
	v_add_u32_e32 v7, 1, v5
	v_fma_f32 v8, -v6, v5, v4
	v_fma_f32 v9, -v7, v5, v4
	v_cmp_ge_f32_e64 s[0:1], 0, v8
	s_nop 1
	v_cndmask_b32_e64 v5, v5, v6, s[0:1]
	v_cmp_lt_f32_e64 s[0:1], 0, v9
	s_nop 1
	v_cndmask_b32_e64 v5, v5, v7, s[0:1]
	v_mul_f32_e32 v6, 0x37800000, v5
; __global__ void __launch_bounds__(512, 2) fwd_megakernel(Args a) {
;     ...
; #pragma unroll
;         for (int j = 0; j < 4; ++j) s += (v[j][0] * v[j][0] + v[j][1] * v[j][1]) + (v[j][2] * v[j][2] + v[j][3] * v[j][3]);
;         const float rs = 1.0f / sqrtf(wave_sum(s) * (1.0f / DM) + EPS);
; #pragma unroll
;         for (int j = 0; j < 4; ++j) { const f32x4 gv = ((const f32x4*)final_norm_g)[lane + 64 * j]; __builtin_nontemporal_store(v[j] * rs * gv, &yr[64 * j]); }
	v_cndmask_b32_e32 v5, v5, v6, vcc
	v_cmp_class_f32_e32 vcc, v4, v21
	s_nop 1
	v_cndmask_b32_e32 v4, v5, v4, vcc
	v_div_scale_f32 v5, s[0:1], v4, v4, 1.0
	v_rcp_f32_e32 v6, v5
	v_div_scale_f32 v7, vcc, 1.0, v4, 1.0
	v_fma_f32 v8, -v5, v6, 1.0
	v_fmac_f32_e32 v6, v8, v6
	v_mul_f32_e32 v8, v7, v6
	v_fma_f32 v9, -v5, v8, v7
	v_fmac_f32_e32 v8, v9, v6
	v_fma_f32 v5, -v5, v8, v7
	v_div_fmas_f32 v5, v5, v6, v8
	v_div_fixup_f32 v4, v5, v4, 1.0
	v_pk_mul_f32 v[216:217], v[4:5], v[216:217] op_sel_hi:[0,1]
	v_pk_mul_f32 v[218:219], v[4:5], v[218:219] op_sel_hi:[0,1]
	v_pk_mul_f32 v[220:221], v[4:5], v[220:221] op_sel_hi:[0,1]
	v_pk_mul_f32 v[222:223], v[4:5], v[222:223] op_sel_hi:[0,1]
	v_pk_mul_f32 v[224:225], v[4:5], v[224:225] op_sel_hi:[0,1]
	v_pk_mul_f32 v[226:227], v[4:5], v[226:227] op_sel_hi:[0,1]
	v_pk_mul_f32 v[228:229], v[4:5], v[228:229] op_sel_hi:[0,1]
	v_pk_mul_f32 v[230:231], v[4:5], v[230:231] op_sel_hi:[0,1]
	v_pk_mul_f32 v[216:217], v[216:217], v[96:97]
	v_pk_mul_f32 v[218:219], v[218:219], v[98:99]
	v_pk_mul_f32 v[220:221], v[220:221], v[100:101]
	v_pk_mul_f32 v[222:223], v[222:223], v[102:103]
	v_pk_mul_f32 v[224:225], v[224:225], v[104:105]
	v_pk_mul_f32 v[226:227], v[226:227], v[106:107]
	v_pk_mul_f32 v[228:229], v[228:229], v[108:109]
	v_pk_mul_f32 v[230:231], v[230:231], v[110:111]
	global_store_dwordx4 v10, v[216:219], s[6:7] offset:0 nt
	global_store_dwordx4 v10, v[220:223], s[6:7] offset:1024 nt
	global_store_dwordx4 v10, v[224:227], s[6:7] offset:2048 nt
	global_store_dwordx4 v10, v[228:231], s[6:7] offset:3072 nt
.Lp9_prompt:
	s_waitcnt vmcnt(12)
	v_pk_mul_f32 v[2:3], v[32:33], v[32:33]
	v_pk_fma_f32 v[2:3], v[34:35], v[34:35], v[2:3]
	v_pk_fma_f32 v[2:3], v[36:37], v[36:37], v[2:3]
	v_pk_fma_f32 v[2:3], v[38:39], v[38:39], v[2:3]
	v_pk_fma_f32 v[2:3], v[40:41], v[40:41], v[2:3]
	v_pk_fma_f32 v[2:3], v[42:43], v[42:43], v[2:3]
	v_pk_fma_f32 v[2:3], v[44:45], v[44:45], v[2:3]
	v_pk_fma_f32 v[2:3], v[46:47], v[46:47], v[2:3]
	v_add_f32_e32 v2, v2, v3
	s_nop 1
	v_add_f32_dpp v2, v2, v2 quad_perm:[1,0,3,2] row_mask:0xf bank_mask:0xf
	s_nop 1
	v_add_f32_dpp v2, v2, v2 quad_perm:[2,3,0,1] row_mask:0xf bank_mask:0xf
	s_nop 1
	v_add_f32_dpp v2, v2, v2 row_half_mirror row_mask:0xf bank_mask:0xf
	s_nop 1
	v_add_f32_dpp v2, v2, v2 row_mirror row_mask:0xf bank_mask:0xf
	s_nop 1
	v_readlane_b32 s20, v2, 0
	v_readlane_b32 s21, v2, 16
	v_readlane_b32 s22, v2, 32
	v_readlane_b32 s23, v2, 48
	s_nop 1
	v_mov_b32_e32 v4, s20
	v_add_f32_e32 v4, s21, v4
	v_add_f32_e32 v4, s22, v4
	v_add_f32_e32 v4, s23, v4
	v_fmamk_f32 v4, v4, 0x3a800000, v20
	v_mul_f32_e32 v5, 0x4f800000, v4
	v_cmp_gt_f32_e32 vcc, s19, v4
	s_nop 1
	v_cndmask_b32_e32 v4, v4, v5, vcc
	v_sqrt_f32_e32 v5, v4
	s_nop 0
	v_add_u32_e32 v6, -1, v5
	v_add_u32_e32 v7, 1, v5
	v_fma_f32 v8, -v6, v5, v4
	v_fma_f32 v9, -v7, v5, v4
	v_cmp_ge_f32_e64 s[0:1], 0, v8
	s_nop 1
	v_cndmask_b32_e64 v5, v5, v6, s[0:1]
	v_cmp_lt_f32_e64 s[0:1], 0, v9
	s_nop 1
	v_cndmask_b32_e64 v5, v5, v7, s[0:1]
	v_mul_f32_e32 v6, 0x37800000, v5
	v_cndmask_b32_e32 v5, v5, v6, vcc
	v_cmp_class_f32_e32 vcc, v4, v21
	s_nop 1
	v_cndmask_b32_e32 v4, v5, v4, vcc
	v_div_scale_f32 v5, s[0:1], v4, v4, 1.0
	v_rcp_f32_e32 v6, v5
	v_div_scale_f32 v7, vcc, 1.0, v4, 1.0
	v_fma_f32 v8, -v5, v6, 1.0
	v_fmac_f32_e32 v6, v8, v6
	v_mul_f32_e32 v8, v7, v6
	v_fma_f32 v9, -v5, v8, v7
	v_fmac_f32_e32 v8, v9, v6
	v_fma_f32 v5, -v5, v8, v7
	v_div_fmas_f32 v5, v5, v6, v8
	v_div_fixup_f32 v4, v5, v4, 1.0
	v_pk_mul_f32 v[32:33], v[4:5], v[32:33] op_sel_hi:[0,1]
	v_pk_mul_f32 v[34:35], v[4:5], v[34:35] op_sel_hi:[0,1]
	v_pk_mul_f32 v[36:37], v[4:5], v[36:37] op_sel_hi:[0,1]
	v_pk_mul_f32 v[38:39], v[4:5], v[38:39] op_sel_hi:[0,1]
	v_pk_mul_f32 v[40:41], v[4:5], v[40:41] op_sel_hi:[0,1]
	v_pk_mul_f32 v[42:43], v[4:5], v[42:43] op_sel_hi:[0,1]
	v_pk_mul_f32 v[44:45], v[4:5], v[44:45] op_sel_hi:[0,1]
	v_pk_mul_f32 v[46:47], v[4:5], v[46:47] op_sel_hi:[0,1]
	v_pk_mul_f32 v[32:33], v[32:33], v[96:97]
	v_pk_mul_f32 v[34:35], v[34:35], v[98:99]
	v_pk_mul_f32 v[36:37], v[36:37], v[100:101]
	v_pk_mul_f32 v[38:39], v[38:39], v[102:103]
	v_pk_mul_f32 v[40:41], v[40:41], v[104:105]
	v_pk_mul_f32 v[42:43], v[42:43], v[106:107]
	v_pk_mul_f32 v[44:45], v[44:45], v[108:109]
	v_pk_mul_f32 v[46:47], v[46:47], v[110:111]
	global_store_dwordx4 v12, v[32:35], s[6:7] offset:0 nt
	global_store_dwordx4 v12, v[36:39], s[6:7] offset:1024 nt
	global_store_dwordx4 v12, v[40:43], s[6:7] offset:2048 nt
	global_store_dwordx4 v12, v[44:47], s[6:7] offset:3072 nt
	v_add_u32_e32 v16, 0x5800000, v0
	global_load_dwordx4 v[32:35], v16, s[6:7] offset:0
	global_load_dwordx4 v[36:39], v16, s[6:7] offset:1024
	global_load_dwordx4 v[40:43], v16, s[6:7] offset:2048
	global_load_dwordx4 v[44:47], v16, s[6:7] offset:3072
	s_waitcnt vmcnt(16)
; #define ws (karg_ws())
; __global__ void __launch_bounds__(512, 2) fwd_megakernel(Args a) {
;     ...
;             for (int j = 0; j < 4; ++j) v[j] = __builtin_nontemporal_load(&yr[64 * j]);
;         } else {
; #pragma unroll
;             for (int j = 0; j < 4; ++j) { const u32x2 w = ((const u32x2*)(X1B + (size_t)r * DM))[lane + 64 * j]; v[j] = (f32x4){bflo(w.x), bfhi(w.x), bflo(w.y), bfhi(w.y)}; }
;         }
;         if (r >= MP) {
;             for (int ks = 0; ks < 11; ++ks) { const f32x4* pr = (const f32x4*)((float*)(ws + WS_PART) + ((size_t)ks * MS + (r - MP)) * DM) + lane;
; #pragma unroll
;                 for (int j = 0; j < 4; ++j) v[j] = v[j] + pr[64 * j]; } }
; #pragma unroll
;         for (int j = 0; j < 4; ++j) s += (v[j][0] * v[j][0] + v[j][1] * v[j][1]) + (v[j][2] * v[j][2] + v[j][3] * v[j][3]);
;         const float rs = 1.0f / sqrtf(wave_sum(s) * (1.0f / DM) + EPS);
; #pragma unroll
;         for (int j = 0; j < 4; ++j) { const f32x4 gv = ((const f32x4*)final_norm_g)[lane + 64 * j]; __builtin_nontemporal_store(v[j] * rs * gv, &yr[64 * j]); }
	v_pk_mul_f32 v[2:3], v[48:49], v[48:49]
	v_pk_fma_f32 v[2:3], v[50:51], v[50:51], v[2:3]
	v_pk_fma_f32 v[2:3], v[52:53], v[52:53], v[2:3]
	v_pk_fma_f32 v[2:3], v[54:55], v[54:55], v[2:3]
	v_pk_fma_f32 v[2:3], v[56:57], v[56:57], v[2:3]
	v_pk_fma_f32 v[2:3], v[58:59], v[58:59], v[2:3]
	v_pk_fma_f32 v[2:3], v[60:61], v[60:61], v[2:3]
	v_pk_fma_f32 v[2:3], v[62:63], v[62:63], v[2:3]
	v_add_f32_e32 v2, v2, v3
	s_nop 1
	v_add_f32_dpp v2, v2, v2 quad_perm:[1,0,3,2] row_mask:0xf bank_mask:0xf
	s_nop 1
	v_add_f32_dpp v2, v2, v2 quad_perm:[2,3,0,1] row_mask:0xf bank_mask:0xf
	s_nop 1
	v_add_f32_dpp v2, v2, v2 row_half_mirror row_mask:0xf bank_mask:0xf
	s_nop 1
	v_add_f32_dpp v2, v2, v2 row_mirror row_mask:0xf bank_mask:0xf
	s_nop 1
	v_readlane_b32 s20, v2, 0
	v_readlane_b32 s21, v2, 16
	v_readlane_b32 s22, v2, 32
	v_readlane_b32 s23, v2, 48
	s_nop 1
	v_mov_b32_e32 v4, s20
	v_add_f32_e32 v4, s21, v4
	v_add_f32_e32 v4, s22, v4
	v_add_f32_e32 v4, s23, v4
	v_fmamk_f32 v4, v4, 0x3a800000, v20
	v_mul_f32_e32 v5, 0x4f800000, v4
	v_cmp_gt_f32_e32 vcc, s19, v4
	s_nop 1
	v_cndmask_b32_e32 v4, v4, v5, vcc
	v_sqrt_f32_e32 v5, v4
	s_nop 0
	v_add_u32_e32 v6, -1, v5
	v_add_u32_e32 v7, 1, v5
	v_fma_f32 v8, -v6, v5, v4
	v_fma_f32 v9, -v7, v5, v4
	v_cmp_ge_f32_e64 s[0:1], 0, v8
	s_nop 1
	v_cndmask_b32_e64 v5, v5, v6, s[0:1]
	v_cmp_lt_f32_e64 s[0:1], 0, v9
	s_nop 1
	v_cndmask_b32_e64 v5, v5, v7, s[0:1]
	v_mul_f32_e32 v6, 0x37800000, v5
	v_cndmask_b32_e32 v5, v5, v6, vcc
	v_cmp_class_f32_e32 vcc, v4, v21
	s_nop 1
	v_cndmask_b32_e32 v4, v5, v4, vcc
	v_div_scale_f32 v5, s[0:1], v4, v4, 1.0
	v_rcp_f32_e32 v6, v5
	v_div_scale_f32 v7, vcc, 1.0, v4, 1.0
	v_fma_f32 v8, -v5, v6, 1.0
	v_fmac_f32_e32 v6, v8, v6
	v_mul_f32_e32 v8, v7, v6
	v_fma_f32 v9, -v5, v8, v7
	v_fmac_f32_e32 v8, v9, v6
	v_fma_f32 v5, -v5, v8, v7
	v_div_fmas_f32 v5, v5, v6, v8
	v_div_fixup_f32 v4, v5, v4, 1.0
	v_pk_mul_f32 v[48:49], v[4:5], v[48:49] op_sel_hi:[0,1]
	v_pk_mul_f32 v[50:51], v[4:5], v[50:51] op_sel_hi:[0,1]
	v_pk_mul_f32 v[52:53], v[4:5], v[52:53] op_sel_hi:[0,1]
	v_pk_mul_f32 v[54:55], v[4:5], v[54:55] op_sel_hi:[0,1]
	v_pk_mul_f32 v[56:57], v[4:5], v[56:57] op_sel_hi:[0,1]
	v_pk_mul_f32 v[58:59], v[4:5], v[58:59] op_sel_hi:[0,1]
	v_pk_mul_f32 v[60:61], v[4:5], v[60:61] op_sel_hi:[0,1]
	v_pk_mul_f32 v[62:63], v[4:5], v[62:63] op_sel_hi:[0,1]
	v_pk_mul_f32 v[48:49], v[48:49], v[96:97]
	v_pk_mul_f32 v[50:51], v[50:51], v[98:99]
	v_pk_mul_f32 v[52:53], v[52:53], v[100:101]
	v_pk_mul_f32 v[54:55], v[54:55], v[102:103]
	v_pk_mul_f32 v[56:57], v[56:57], v[104:105]
	v_pk_mul_f32 v[58:59], v[58:59], v[106:107]
	v_pk_mul_f32 v[60:61], v[60:61], v[108:109]
	v_pk_mul_f32 v[62:63], v[62:63], v[110:111]
	global_store_dwordx4 v13, v[48:51], s[6:7] offset:0 nt
	global_store_dwordx4 v13, v[52:55], s[6:7] offset:1024 nt
	global_store_dwordx4 v13, v[56:59], s[6:7] offset:2048 nt
	global_store_dwordx4 v13, v[60:63], s[6:7] offset:3072 nt
	v_add_u32_e32 v17, 0x5000000, v0
	global_load_dwordx4 v[48:51], v17, s[6:7] offset:0
	global_load_dwordx4 v[52:55], v17, s[6:7] offset:1024
	global_load_dwordx4 v[56:59], v17, s[6:7] offset:2048
	global_load_dwordx4 v[60:63], v17, s[6:7] offset:3072
	s_waitcnt vmcnt(20)
	v_pk_mul_f32 v[2:3], v[64:65], v[64:65]
	v_pk_fma_f32 v[2:3], v[66:67], v[66:67], v[2:3]
	v_pk_fma_f32 v[2:3], v[68:69], v[68:69], v[2:3]
	v_pk_fma_f32 v[2:3], v[70:71], v[70:71], v[2:3]
	v_pk_fma_f32 v[2:3], v[72:73], v[72:73], v[2:3]
	v_pk_fma_f32 v[2:3], v[74:75], v[74:75], v[2:3]
	v_pk_fma_f32 v[2:3], v[76:77], v[76:77], v[2:3]
	v_pk_fma_f32 v[2:3], v[78:79], v[78:79], v[2:3]
	v_add_f32_e32 v2, v2, v3
	s_nop 1
	v_add_f32_dpp v2, v2, v2 quad_perm:[1,0,3,2] row_mask:0xf bank_mask:0xf
	s_nop 1
	v_add_f32_dpp v2, v2, v2 quad_perm:[2,3,0,1] row_mask:0xf bank_mask:0xf
	s_nop 1
	v_add_f32_dpp v2, v2, v2 row_half_mirror row_mask:0xf bank_mask:0xf
	s_nop 1
	v_add_f32_dpp v2, v2, v2 row_mirror row_mask:0xf bank_mask:0xf
	s_nop 1
	v_readlane_b32 s20, v2, 0
	v_readlane_b32 s21, v2, 16
	v_readlane_b32 s22, v2, 32
	v_readlane_b32 s23, v2, 48
	s_nop 1
	v_mov_b32_e32 v4, s20
	v_add_f32_e32 v4, s21, v4
	v_add_f32_e32 v4, s22, v4
	v_add_f32_e32 v4, s23, v4
	v_fmamk_f32 v4, v4, 0x3a800000, v20
	v_mul_f32_e32 v5, 0x4f800000, v4
	v_cmp_gt_f32_e32 vcc, s19, v4
	s_nop 1
	v_cndmask_b32_e32 v4, v4, v5, vcc
	v_sqrt_f32_e32 v5, v4
	s_nop 0
	v_add_u32_e32 v6, -1, v5
	v_add_u32_e32 v7, 1, v5
	v_fma_f32 v8, -v6, v5, v4
	v_fma_f32 v9, -v7, v5, v4
	v_cmp_ge_f32_e64 s[0:1], 0, v8
	s_nop 1
	v_cndmask_b32_e64 v5, v5, v6, s[0:1]
	v_cmp_lt_f32_e64 s[0:1], 0, v9
	s_nop 1
	v_cndmask_b32_e64 v5, v5, v7, s[0:1]
	v_mul_f32_e32 v6, 0x37800000, v5
	v_cndmask_b32_e32 v5, v5, v6, vcc
	v_cmp_class_f32_e32 vcc, v4, v21
	s_nop 1
	v_cndmask_b32_e32 v4, v5, v4, vcc
	v_div_scale_f32 v5, s[0:1], v4, v4, 1.0
	v_rcp_f32_e32 v6, v5
	v_div_scale_f32 v7, vcc, 1.0, v4, 1.0
	v_fma_f32 v8, -v5, v6, 1.0
	v_fmac_f32_e32 v6, v8, v6
	v_mul_f32_e32 v8, v7, v6
	v_fma_f32 v9, -v5, v8, v7
	v_fmac_f32_e32 v8, v9, v6
	v_fma_f32 v5, -v5, v8, v7
	v_div_fmas_f32 v5, v5, v6, v8
	v_div_fixup_f32 v4, v5, v4, 1.0
	v_pk_mul_f32 v[64:65], v[4:5], v[64:65] op_sel_hi:[0,1]
	v_pk_mul_f32 v[66:67], v[4:5], v[66:67] op_sel_hi:[0,1]
	v_pk_mul_f32 v[68:69], v[4:5], v[68:69] op_sel_hi:[0,1]
	v_pk_mul_f32 v[70:71], v[4:5], v[70:71] op_sel_hi:[0,1]
	v_pk_mul_f32 v[72:73], v[4:5], v[72:73] op_sel_hi:[0,1]
	v_pk_mul_f32 v[74:75], v[4:5], v[74:75] op_sel_hi:[0,1]
	v_pk_mul_f32 v[76:77], v[4:5], v[76:77] op_sel_hi:[0,1]
	v_pk_mul_f32 v[78:79], v[4:5], v[78:79] op_sel_hi:[0,1]
	v_pk_mul_f32 v[64:65], v[64:65], v[96:97]
	v_pk_mul_f32 v[66:67], v[66:67], v[98:99]
	v_pk_mul_f32 v[68:69], v[68:69], v[100:101]
	v_pk_mul_f32 v[70:71], v[70:71], v[102:103]
	v_pk_mul_f32 v[72:73], v[72:73], v[104:105]
	v_pk_mul_f32 v[74:75], v[74:75], v[106:107]
	v_pk_mul_f32 v[76:77], v[76:77], v[108:109]
	v_pk_mul_f32 v[78:79], v[78:79], v[110:111]
	global_store_dwordx4 v14, v[64:67], s[6:7] offset:0 nt
	global_store_dwordx4 v14, v[68:71], s[6:7] offset:1024 nt
	global_store_dwordx4 v14, v[72:75], s[6:7] offset:2048 nt
	global_store_dwordx4 v14, v[76:79], s[6:7] offset:3072 nt
	v_add_u32_e32 v18, 0x4800000, v0
	global_load_dwordx4 v[64:67], v18, s[6:7] offset:0
	global_load_dwordx4 v[68:71], v18, s[6:7] offset:1024
	global_load_dwordx4 v[72:75], v18, s[6:7] offset:2048
	global_load_dwordx4 v[76:79], v18, s[6:7] offset:3072
	s_waitcnt vmcnt(24)
; #define ws (karg_ws())
; __global__ void __launch_bounds__(512, 2) fwd_megakernel(Args a) {
;     ...
;             for (int j = 0; j < 4; ++j) v[j] = __builtin_nontemporal_load(&yr[64 * j]);
;         } else {
; #pragma unroll
;             for (int j = 0; j < 4; ++j) { const u32x2 w = ((const u32x2*)(X1B + (size_t)r * DM))[lane + 64 * j]; v[j] = (f32x4){bflo(w.x), bfhi(w.x), bflo(w.y), bfhi(w.y)}; }
;         }
;         if (r >= MP) {
;             for (int ks = 0; ks < 11; ++ks) { const f32x4* pr = (const f32x4*)((float*)(ws + WS_PART) + ((size_t)ks * MS + (r - MP)) * DM) + lane;
; #pragma unroll
;                 for (int j = 0; j < 4; ++j) v[j] = v[j] + pr[64 * j]; } }
; #pragma unroll
;         for (int j = 0; j < 4; ++j) s += (v[j][0] * v[j][0] + v[j][1] * v[j][1]) + (v[j][2] * v[j][2] + v[j][3] * v[j][3]);
;         const float rs = 1.0f / sqrtf(wave_sum(s) * (1.0f / DM) + EPS);
; #pragma unroll
;         for (int j = 0; j < 4; ++j) { const f32x4 gv = ((const f32x4*)final_norm_g)[lane + 64 * j]; __builtin_nontemporal_store(v[j] * rs * gv, &yr[64 * j]); }
	v_pk_mul_f32 v[2:3], v[80:81], v[80:81]
	v_pk_fma_f32 v[2:3], v[82:83], v[82:83], v[2:3]
	v_pk_fma_f32 v[2:3], v[84:85], v[84:85], v[2:3]
	v_pk_fma_f32 v[2:3], v[86:87], v[86:87], v[2:3]
	v_pk_fma_f32 v[2:3], v[88:89], v[88:89], v[2:3]
	v_pk_fma_f32 v[2:3], v[90:91], v[90:91], v[2:3]
	v_pk_fma_f32 v[2:3], v[92:93], v[92:93], v[2:3]
	v_pk_fma_f32 v[2:3], v[94:95], v[94:95], v[2:3]
	v_add_f32_e32 v2, v2, v3
	s_nop 1
	v_add_f32_dpp v2, v2, v2 quad_perm:[1,0,3,2] row_mask:0xf bank_mask:0xf
	s_nop 1
	v_add_f32_dpp v2, v2, v2 quad_perm:[2,3,0,1] row_mask:0xf bank_mask:0xf
	s_nop 1
	v_add_f32_dpp v2, v2, v2 row_half_mirror row_mask:0xf bank_mask:0xf
	s_nop 1
	v_add_f32_dpp v2, v2, v2 row_mirror row_mask:0xf bank_mask:0xf
	s_nop 1
	v_readlane_b32 s20, v2, 0
	v_readlane_b32 s21, v2, 16
	v_readlane_b32 s22, v2, 32
	v_readlane_b32 s23, v2, 48
	s_nop 1
	v_mov_b32_e32 v4, s20
	v_add_f32_e32 v4, s21, v4
	v_add_f32_e32 v4, s22, v4
	v_add_f32_e32 v4, s23, v4
	v_fmamk_f32 v4, v4, 0x3a800000, v20
	v_mul_f32_e32 v5, 0x4f800000, v4
	v_cmp_gt_f32_e32 vcc, s19, v4
	s_nop 1
	v_cndmask_b32_e32 v4, v4, v5, vcc
	v_sqrt_f32_e32 v5, v4
	s_nop 0
	v_add_u32_e32 v6, -1, v5
	v_add_u32_e32 v7, 1, v5
	v_fma_f32 v8, -v6, v5, v4
	v_fma_f32 v9, -v7, v5, v4
	v_cmp_ge_f32_e64 s[0:1], 0, v8
	s_nop 1
	v_cndmask_b32_e64 v5, v5, v6, s[0:1]
	v_cmp_lt_f32_e64 s[0:1], 0, v9
	s_nop 1
	v_cndmask_b32_e64 v5, v5, v7, s[0:1]
	v_mul_f32_e32 v6, 0x37800000, v5
	v_cndmask_b32_e32 v5, v5, v6, vcc
	v_cmp_class_f32_e32 vcc, v4, v21
	s_nop 1
	v_cndmask_b32_e32 v4, v5, v4, vcc
	v_div_scale_f32 v5, s[0:1], v4, v4, 1.0
	v_rcp_f32_e32 v6, v5
	v_div_scale_f32 v7, vcc, 1.0, v4, 1.0
	v_fma_f32 v8, -v5, v6, 1.0
	v_fmac_f32_e32 v6, v8, v6
	v_mul_f32_e32 v8, v7, v6
	v_fma_f32 v9, -v5, v8, v7
	v_fmac_f32_e32 v8, v9, v6
	v_fma_f32 v5, -v5, v8, v7
	v_div_fmas_f32 v5, v5, v6, v8
	v_div_fixup_f32 v4, v5, v4, 1.0
	v_pk_mul_f32 v[80:81], v[4:5], v[80:81] op_sel_hi:[0,1]
	v_pk_mul_f32 v[82:83], v[4:5], v[82:83] op_sel_hi:[0,1]
	v_pk_mul_f32 v[84:85], v[4:5], v[84:85] op_sel_hi:[0,1]
	v_pk_mul_f32 v[86:87], v[4:5], v[86:87] op_sel_hi:[0,1]
	v_pk_mul_f32 v[88:89], v[4:5], v[88:89] op_sel_hi:[0,1]
	v_pk_mul_f32 v[90:91], v[4:5], v[90:91] op_sel_hi:[0,1]
	v_pk_mul_f32 v[92:93], v[4:5], v[92:93] op_sel_hi:[0,1]
	v_pk_mul_f32 v[94:95], v[4:5], v[94:95] op_sel_hi:[0,1]
	v_pk_mul_f32 v[80:81], v[80:81], v[96:97]
	v_pk_mul_f32 v[82:83], v[82:83], v[98:99]
	v_pk_mul_f32 v[84:85], v[84:85], v[100:101]
	v_pk_mul_f32 v[86:87], v[86:87], v[102:103]
	v_pk_mul_f32 v[88:89], v[88:89], v[104:105]
	v_pk_mul_f32 v[90:91], v[90:91], v[106:107]
	v_pk_mul_f32 v[92:93], v[92:93], v[108:109]
	v_pk_mul_f32 v[94:95], v[94:95], v[110:111]
	global_store_dwordx4 v15, v[80:83], s[6:7] offset:0 nt
	global_store_dwordx4 v15, v[84:87], s[6:7] offset:1024 nt
	global_store_dwordx4 v15, v[88:91], s[6:7] offset:2048 nt
	global_store_dwordx4 v15, v[92:95], s[6:7] offset:3072 nt
	v_add_u32_e32 v19, 0x4000000, v0
	global_load_dwordx4 v[80:83], v19, s[6:7] offset:0
	global_load_dwordx4 v[84:87], v19, s[6:7] offset:1024
	global_load_dwordx4 v[88:91], v19, s[6:7] offset:2048
	global_load_dwordx4 v[92:95], v19, s[6:7] offset:3072
	s_waitcnt vmcnt(24)
	v_pk_mul_f32 v[2:3], v[32:33], v[32:33]
	v_pk_fma_f32 v[2:3], v[34:35], v[34:35], v[2:3]
	v_pk_fma_f32 v[2:3], v[36:37], v[36:37], v[2:3]
	v_pk_fma_f32 v[2:3], v[38:39], v[38:39], v[2:3]
	v_pk_fma_f32 v[2:3], v[40:41], v[40:41], v[2:3]
	v_pk_fma_f32 v[2:3], v[42:43], v[42:43], v[2:3]
	v_pk_fma_f32 v[2:3], v[44:45], v[44:45], v[2:3]
	v_pk_fma_f32 v[2:3], v[46:47], v[46:47], v[2:3]
	v_add_f32_e32 v2, v2, v3
	s_nop 1
	v_add_f32_dpp v2, v2, v2 quad_perm:[1,0,3,2] row_mask:0xf bank_mask:0xf
	s_nop 1
	v_add_f32_dpp v2, v2, v2 quad_perm:[2,3,0,1] row_mask:0xf bank_mask:0xf
	s_nop 1
	v_add_f32_dpp v2, v2, v2 row_half_mirror row_mask:0xf bank_mask:0xf
	s_nop 1
	v_add_f32_dpp v2, v2, v2 row_mirror row_mask:0xf bank_mask:0xf
	s_nop 1
	v_readlane_b32 s20, v2, 0
	v_readlane_b32 s21, v2, 16
	v_readlane_b32 s22, v2, 32
	v_readlane_b32 s23, v2, 48
	s_nop 1
	v_mov_b32_e32 v4, s20
	v_add_f32_e32 v4, s21, v4
	v_add_f32_e32 v4, s22, v4
	v_add_f32_e32 v4, s23, v4
	v_fmamk_f32 v4, v4, 0x3a800000, v20
	v_mul_f32_e32 v5, 0x4f800000, v4
	v_cmp_gt_f32_e32 vcc, s19, v4
	s_nop 1
	v_cndmask_b32_e32 v4, v4, v5, vcc
	v_sqrt_f32_e32 v5, v4
	s_nop 0
	v_add_u32_e32 v6, -1, v5
	v_add_u32_e32 v7, 1, v5
	v_fma_f32 v8, -v6, v5, v4
	v_fma_f32 v9, -v7, v5, v4
	v_cmp_ge_f32_e64 s[0:1], 0, v8
	s_nop 1
	v_cndmask_b32_e64 v5, v5, v6, s[0:1]
	v_cmp_lt_f32_e64 s[0:1], 0, v9
	s_nop 1
	v_cndmask_b32_e64 v5, v5, v7, s[0:1]
	v_mul_f32_e32 v6, 0x37800000, v5
	v_cndmask_b32_e32 v5, v5, v6, vcc
	v_cmp_class_f32_e32 vcc, v4, v21
	s_nop 1
	v_cndmask_b32_e32 v4, v5, v4, vcc
	v_div_scale_f32 v5, s[0:1], v4, v4, 1.0
	v_rcp_f32_e32 v6, v5
	v_div_scale_f32 v7, vcc, 1.0, v4, 1.0
	v_fma_f32 v8, -v5, v6, 1.0
	v_fmac_f32_e32 v6, v8, v6
	v_mul_f32_e32 v8, v7, v6
	v_fma_f32 v9, -v5, v8, v7
	v_fmac_f32_e32 v8, v9, v6
	v_fma_f32 v5, -v5, v8, v7
	v_div_fmas_f32 v5, v5, v6, v8
	v_div_fixup_f32 v4, v5, v4, 1.0
	v_pk_mul_f32 v[32:33], v[4:5], v[32:33] op_sel_hi:[0,1]
	v_pk_mul_f32 v[34:35], v[4:5], v[34:35] op_sel_hi:[0,1]
	v_pk_mul_f32 v[36:37], v[4:5], v[36:37] op_sel_hi:[0,1]
	v_pk_mul_f32 v[38:39], v[4:5], v[38:39] op_sel_hi:[0,1]
	v_pk_mul_f32 v[40:41], v[4:5], v[40:41] op_sel_hi:[0,1]
	v_pk_mul_f32 v[42:43], v[4:5], v[42:43] op_sel_hi:[0,1]
	v_pk_mul_f32 v[44:45], v[4:5], v[44:45] op_sel_hi:[0,1]
	v_pk_mul_f32 v[46:47], v[4:5], v[46:47] op_sel_hi:[0,1]
	v_pk_mul_f32 v[32:33], v[32:33], v[96:97]
	v_pk_mul_f32 v[34:35], v[34:35], v[98:99]
	v_pk_mul_f32 v[36:37], v[36:37], v[100:101]
	v_pk_mul_f32 v[38:39], v[38:39], v[102:103]
	v_pk_mul_f32 v[40:41], v[40:41], v[104:105]
	v_pk_mul_f32 v[42:43], v[42:43], v[106:107]
	v_pk_mul_f32 v[44:45], v[44:45], v[108:109]
	v_pk_mul_f32 v[46:47], v[46:47], v[110:111]
	global_store_dwordx4 v16, v[32:35], s[6:7] offset:0 nt
	global_store_dwordx4 v16, v[36:39], s[6:7] offset:1024 nt
	global_store_dwordx4 v16, v[40:43], s[6:7] offset:2048 nt
	global_store_dwordx4 v16, v[44:47], s[6:7] offset:3072 nt
	v_add_u32_e32 v12, 0x3800000, v0
	global_load_dwordx4 v[32:35], v12, s[6:7] offset:0
	global_load_dwordx4 v[36:39], v12, s[6:7] offset:1024
	global_load_dwordx4 v[40:43], v12, s[6:7] offset:2048
	global_load_dwordx4 v[44:47], v12, s[6:7] offset:3072
	s_waitcnt vmcnt(24)
; #define ws (karg_ws())
; __global__ void __launch_bounds__(512, 2) fwd_megakernel(Args a) {
;     ...
;             for (int j = 0; j < 4; ++j) v[j] = __builtin_nontemporal_load(&yr[64 * j]);
;         } else {
; #pragma unroll
;             for (int j = 0; j < 4; ++j) { const u32x2 w = ((const u32x2*)(X1B + (size_t)r * DM))[lane + 64 * j]; v[j] = (f32x4){bflo(w.x), bfhi(w.x), bflo(w.y), bfhi(w.y)}; }
;         }
;         if (r >= MP) {
;             for (int ks = 0; ks < 11; ++ks) { const f32x4* pr = (const f32x4*)((float*)(ws + WS_PART) + ((size_t)ks * MS + (r - MP)) * DM) + lane;
; #pragma unroll
;                 for (int j = 0; j < 4; ++j) v[j] = v[j] + pr[64 * j]; } }
; #pragma unroll
;         for (int j = 0; j < 4; ++j) s += (v[j][0] * v[j][0] + v[j][1] * v[j][1]) + (v[j][2] * v[j][2] + v[j][3] * v[j][3]);
;         const float rs = 1.0f / sqrtf(wave_sum(s) * (1.0f / DM) + EPS);
; #pragma unroll
;         for (int j = 0; j < 4; ++j) { const f32x4 gv = ((const f32x4*)final_norm_g)[lane + 64 * j]; __builtin_nontemporal_store(v[j] * rs * gv, &yr[64 * j]); }
	v_pk_mul_f32 v[2:3], v[48:49], v[48:49]
	v_pk_fma_f32 v[2:3], v[50:51], v[50:51], v[2:3]
	v_pk_fma_f32 v[2:3], v[52:53], v[52:53], v[2:3]
	v_pk_fma_f32 v[2:3], v[54:55], v[54:55], v[2:3]
	v_pk_fma_f32 v[2:3], v[56:57], v[56:57], v[2:3]
	v_pk_fma_f32 v[2:3], v[58:59], v[58:59], v[2:3]
	v_pk_fma_f32 v[2:3], v[60:61], v[60:61], v[2:3]
	v_pk_fma_f32 v[2:3], v[62:63], v[62:63], v[2:3]
	v_add_f32_e32 v2, v2, v3
	s_nop 1
	v_add_f32_dpp v2, v2, v2 quad_perm:[1,0,3,2] row_mask:0xf bank_mask:0xf
	s_nop 1
	v_add_f32_dpp v2, v2, v2 quad_perm:[2,3,0,1] row_mask:0xf bank_mask:0xf
	s_nop 1
	v_add_f32_dpp v2, v2, v2 row_half_mirror row_mask:0xf bank_mask:0xf
	s_nop 1
	v_add_f32_dpp v2, v2, v2 row_mirror row_mask:0xf bank_mask:0xf
	s_nop 1
	v_readlane_b32 s20, v2, 0
	v_readlane_b32 s21, v2, 16
	v_readlane_b32 s22, v2, 32
	v_readlane_b32 s23, v2, 48
	s_nop 1
	v_mov_b32_e32 v4, s20
	v_add_f32_e32 v4, s21, v4
	v_add_f32_e32 v4, s22, v4
	v_add_f32_e32 v4, s23, v4
	v_fmamk_f32 v4, v4, 0x3a800000, v20
	v_mul_f32_e32 v5, 0x4f800000, v4
	v_cmp_gt_f32_e32 vcc, s19, v4
	s_nop 1
	v_cndmask_b32_e32 v4, v4, v5, vcc
	v_sqrt_f32_e32 v5, v4
	s_nop 0
	v_add_u32_e32 v6, -1, v5
	v_add_u32_e32 v7, 1, v5
	v_fma_f32 v8, -v6, v5, v4
	v_fma_f32 v9, -v7, v5, v4
	v_cmp_ge_f32_e64 s[0:1], 0, v8
	s_nop 1
	v_cndmask_b32_e64 v5, v5, v6, s[0:1]
	v_cmp_lt_f32_e64 s[0:1], 0, v9
	s_nop 1
	v_cndmask_b32_e64 v5, v5, v7, s[0:1]
	v_mul_f32_e32 v6, 0x37800000, v5
	v_cndmask_b32_e32 v5, v5, v6, vcc
	v_cmp_class_f32_e32 vcc, v4, v21
	s_nop 1
	v_cndmask_b32_e32 v4, v5, v4, vcc
	v_div_scale_f32 v5, s[0:1], v4, v4, 1.0
	v_rcp_f32_e32 v6, v5
	v_div_scale_f32 v7, vcc, 1.0, v4, 1.0
	v_fma_f32 v8, -v5, v6, 1.0
	v_fmac_f32_e32 v6, v8, v6
	v_mul_f32_e32 v8, v7, v6
	v_fma_f32 v9, -v5, v8, v7
	v_fmac_f32_e32 v8, v9, v6
	v_fma_f32 v5, -v5, v8, v7
	v_div_fmas_f32 v5, v5, v6, v8
	v_div_fixup_f32 v4, v5, v4, 1.0
	v_pk_mul_f32 v[48:49], v[4:5], v[48:49] op_sel_hi:[0,1]
	v_pk_mul_f32 v[50:51], v[4:5], v[50:51] op_sel_hi:[0,1]
	v_pk_mul_f32 v[52:53], v[4:5], v[52:53] op_sel_hi:[0,1]
	v_pk_mul_f32 v[54:55], v[4:5], v[54:55] op_sel_hi:[0,1]
	v_pk_mul_f32 v[56:57], v[4:5], v[56:57] op_sel_hi:[0,1]
	v_pk_mul_f32 v[58:59], v[4:5], v[58:59] op_sel_hi:[0,1]
	v_pk_mul_f32 v[60:61], v[4:5], v[60:61] op_sel_hi:[0,1]
	v_pk_mul_f32 v[62:63], v[4:5], v[62:63] op_sel_hi:[0,1]
	v_pk_mul_f32 v[48:49], v[48:49], v[96:97]
	v_pk_mul_f32 v[50:51], v[50:51], v[98:99]
	v_pk_mul_f32 v[52:53], v[52:53], v[100:101]
	v_pk_mul_f32 v[54:55], v[54:55], v[102:103]
	v_pk_mul_f32 v[56:57], v[56:57], v[104:105]
	v_pk_mul_f32 v[58:59], v[58:59], v[106:107]
	v_pk_mul_f32 v[60:61], v[60:61], v[108:109]
	v_pk_mul_f32 v[62:63], v[62:63], v[110:111]
	global_store_dwordx4 v17, v[48:51], s[6:7] offset:0 nt
	global_store_dwordx4 v17, v[52:55], s[6:7] offset:1024 nt
	global_store_dwordx4 v17, v[56:59], s[6:7] offset:2048 nt
	global_store_dwordx4 v17, v[60:63], s[6:7] offset:3072 nt
	v_add_u32_e32 v13, 0x3000000, v0
	global_load_dwordx4 v[48:51], v13, s[6:7] offset:0
	global_load_dwordx4 v[52:55], v13, s[6:7] offset:1024
	global_load_dwordx4 v[56:59], v13, s[6:7] offset:2048
	global_load_dwordx4 v[60:63], v13, s[6:7] offset:3072
	s_waitcnt vmcnt(24)
	v_pk_mul_f32 v[2:3], v[64:65], v[64:65]
	v_pk_fma_f32 v[2:3], v[66:67], v[66:67], v[2:3]
	v_pk_fma_f32 v[2:3], v[68:69], v[68:69], v[2:3]
	v_pk_fma_f32 v[2:3], v[70:71], v[70:71], v[2:3]
	v_pk_fma_f32 v[2:3], v[72:73], v[72:73], v[2:3]
	v_pk_fma_f32 v[2:3], v[74:75], v[74:75], v[2:3]
	v_pk_fma_f32 v[2:3], v[76:77], v[76:77], v[2:3]
	v_pk_fma_f32 v[2:3], v[78:79], v[78:79], v[2:3]
	v_add_f32_e32 v2, v2, v3
	s_nop 1
	v_add_f32_dpp v2, v2, v2 quad_perm:[1,0,3,2] row_mask:0xf bank_mask:0xf
	s_nop 1
	v_add_f32_dpp v2, v2, v2 quad_perm:[2,3,0,1] row_mask:0xf bank_mask:0xf
	s_nop 1
	v_add_f32_dpp v2, v2, v2 row_half_mirror row_mask:0xf bank_mask:0xf
	s_nop 1
	v_add_f32_dpp v2, v2, v2 row_mirror row_mask:0xf bank_mask:0xf
	s_nop 1
	v_readlane_b32 s20, v2, 0
	v_readlane_b32 s21, v2, 16
	v_readlane_b32 s22, v2, 32
	v_readlane_b32 s23, v2, 48
	s_nop 1
	v_mov_b32_e32 v4, s20
	v_add_f32_e32 v4, s21, v4
	v_add_f32_e32 v4, s22, v4
	v_add_f32_e32 v4, s23, v4
	v_fmamk_f32 v4, v4, 0x3a800000, v20
	v_mul_f32_e32 v5, 0x4f800000, v4
	v_cmp_gt_f32_e32 vcc, s19, v4
	s_nop 1
	v_cndmask_b32_e32 v4, v4, v5, vcc
	v_sqrt_f32_e32 v5, v4
	s_nop 0
	v_add_u32_e32 v6, -1, v5
	v_add_u32_e32 v7, 1, v5
	v_fma_f32 v8, -v6, v5, v4
	v_fma_f32 v9, -v7, v5, v4
	v_cmp_ge_f32_e64 s[0:1], 0, v8
	s_nop 1
	v_cndmask_b32_e64 v5, v5, v6, s[0:1]
	v_cmp_lt_f32_e64 s[0:1], 0, v9
	s_nop 1
	v_cndmask_b32_e64 v5, v5, v7, s[0:1]
	v_mul_f32_e32 v6, 0x37800000, v5
	v_cndmask_b32_e32 v5, v5, v6, vcc
	v_cmp_class_f32_e32 vcc, v4, v21
	s_nop 1
	v_cndmask_b32_e32 v4, v5, v4, vcc
	v_div_scale_f32 v5, s[0:1], v4, v4, 1.0
	v_rcp_f32_e32 v6, v5
	v_div_scale_f32 v7, vcc, 1.0, v4, 1.0
	v_fma_f32 v8, -v5, v6, 1.0
	v_fmac_f32_e32 v6, v8, v6
	v_mul_f32_e32 v8, v7, v6
	v_fma_f32 v9, -v5, v8, v7
	v_fmac_f32_e32 v8, v9, v6
	v_fma_f32 v5, -v5, v8, v7
	v_div_fmas_f32 v5, v5, v6, v8
	v_div_fixup_f32 v4, v5, v4, 1.0
	v_pk_mul_f32 v[64:65], v[4:5], v[64:65] op_sel_hi:[0,1]
	v_pk_mul_f32 v[66:67], v[4:5], v[66:67] op_sel_hi:[0,1]
	v_pk_mul_f32 v[68:69], v[4:5], v[68:69] op_sel_hi:[0,1]
	v_pk_mul_f32 v[70:71], v[4:5], v[70:71] op_sel_hi:[0,1]
	v_pk_mul_f32 v[72:73], v[4:5], v[72:73] op_sel_hi:[0,1]
	v_pk_mul_f32 v[74:75], v[4:5], v[74:75] op_sel_hi:[0,1]
	v_pk_mul_f32 v[76:77], v[4:5], v[76:77] op_sel_hi:[0,1]
	v_pk_mul_f32 v[78:79], v[4:5], v[78:79] op_sel_hi:[0,1]
	v_pk_mul_f32 v[64:65], v[64:65], v[96:97]
	v_pk_mul_f32 v[66:67], v[66:67], v[98:99]
	v_pk_mul_f32 v[68:69], v[68:69], v[100:101]
	v_pk_mul_f32 v[70:71], v[70:71], v[102:103]
	v_pk_mul_f32 v[72:73], v[72:73], v[104:105]
	v_pk_mul_f32 v[74:75], v[74:75], v[106:107]
	v_pk_mul_f32 v[76:77], v[76:77], v[108:109]
	v_pk_mul_f32 v[78:79], v[78:79], v[110:111]
	global_store_dwordx4 v18, v[64:67], s[6:7] offset:0 nt
	global_store_dwordx4 v18, v[68:71], s[6:7] offset:1024 nt
	global_store_dwordx4 v18, v[72:75], s[6:7] offset:2048 nt
	global_store_dwordx4 v18, v[76:79], s[6:7] offset:3072 nt
	v_add_u32_e32 v14, 0x2800000, v0
	global_load_dwordx4 v[64:67], v14, s[6:7] offset:0
	global_load_dwordx4 v[68:71], v14, s[6:7] offset:1024
	global_load_dwordx4 v[72:75], v14, s[6:7] offset:2048
	global_load_dwordx4 v[76:79], v14, s[6:7] offset:3072
	s_waitcnt vmcnt(24)
; #define ws (karg_ws())
; __global__ void __launch_bounds__(512, 2) fwd_megakernel(Args a) {
;     ...
;             for (int j = 0; j < 4; ++j) v[j] = __builtin_nontemporal_load(&yr[64 * j]);
;         } else {
; #pragma unroll
;             for (int j = 0; j < 4; ++j) { const u32x2 w = ((const u32x2*)(X1B + (size_t)r * DM))[lane + 64 * j]; v[j] = (f32x4){bflo(w.x), bfhi(w.x), bflo(w.y), bfhi(w.y)}; }
;         }
;         if (r >= MP) {
;             for (int ks = 0; ks < 11; ++ks) { const f32x4* pr = (const f32x4*)((float*)(ws + WS_PART) + ((size_t)ks * MS + (r - MP)) * DM) + lane;
; #pragma unroll
;                 for (int j = 0; j < 4; ++j) v[j] = v[j] + pr[64 * j]; } }
; #pragma unroll
;         for (int j = 0; j < 4; ++j) s += (v[j][0] * v[j][0] + v[j][1] * v[j][1]) + (v[j][2] * v[j][2] + v[j][3] * v[j][3]);
;         const float rs = 1.0f / sqrtf(wave_sum(s) * (1.0f / DM) + EPS);
; #pragma unroll
;         for (int j = 0; j < 4; ++j) { const f32x4 gv = ((const f32x4*)final_norm_g)[lane + 64 * j]; __builtin_nontemporal_store(v[j] * rs * gv, &yr[64 * j]); }
	v_pk_mul_f32 v[2:3], v[80:81], v[80:81]
	v_pk_fma_f32 v[2:3], v[82:83], v[82:83], v[2:3]
	v_pk_fma_f32 v[2:3], v[84:85], v[84:85], v[2:3]
	v_pk_fma_f32 v[2:3], v[86:87], v[86:87], v[2:3]
	v_pk_fma_f32 v[2:3], v[88:89], v[88:89], v[2:3]
	v_pk_fma_f32 v[2:3], v[90:91], v[90:91], v[2:3]
	v_pk_fma_f32 v[2:3], v[92:93], v[92:93], v[2:3]
	v_pk_fma_f32 v[2:3], v[94:95], v[94:95], v[2:3]
	v_add_f32_e32 v2, v2, v3
	s_nop 1
	v_add_f32_dpp v2, v2, v2 quad_perm:[1,0,3,2] row_mask:0xf bank_mask:0xf
	s_nop 1
	v_add_f32_dpp v2, v2, v2 quad_perm:[2,3,0,1] row_mask:0xf bank_mask:0xf
	s_nop 1
	v_add_f32_dpp v2, v2, v2 row_half_mirror row_mask:0xf bank_mask:0xf
	s_nop 1
	v_add_f32_dpp v2, v2, v2 row_mirror row_mask:0xf bank_mask:0xf
	s_nop 1
	v_readlane_b32 s20, v2, 0
	v_readlane_b32 s21, v2, 16
	v_readlane_b32 s22, v2, 32
	v_readlane_b32 s23, v2, 48
	s_nop 1
	v_mov_b32_e32 v4, s20
	v_add_f32_e32 v4, s21, v4
	v_add_f32_e32 v4, s22, v4
	v_add_f32_e32 v4, s23, v4
	v_fmamk_f32 v4, v4, 0x3a800000, v20
	v_mul_f32_e32 v5, 0x4f800000, v4
	v_cmp_gt_f32_e32 vcc, s19, v4
	s_nop 1
	v_cndmask_b32_e32 v4, v4, v5, vcc
	v_sqrt_f32_e32 v5, v4
	s_nop 0
	v_add_u32_e32 v6, -1, v5
	v_add_u32_e32 v7, 1, v5
	v_fma_f32 v8, -v6, v5, v4
	v_fma_f32 v9, -v7, v5, v4
	v_cmp_ge_f32_e64 s[0:1], 0, v8
	s_nop 1
	v_cndmask_b32_e64 v5, v5, v6, s[0:1]
	v_cmp_lt_f32_e64 s[0:1], 0, v9
	s_nop 1
	v_cndmask_b32_e64 v5, v5, v7, s[0:1]
	v_mul_f32_e32 v6, 0x37800000, v5
	v_cndmask_b32_e32 v5, v5, v6, vcc
	v_cmp_class_f32_e32 vcc, v4, v21
	s_nop 1
	v_cndmask_b32_e32 v4, v5, v4, vcc
	v_div_scale_f32 v5, s[0:1], v4, v4, 1.0
	v_rcp_f32_e32 v6, v5
	v_div_scale_f32 v7, vcc, 1.0, v4, 1.0
	v_fma_f32 v8, -v5, v6, 1.0
	v_fmac_f32_e32 v6, v8, v6
	v_mul_f32_e32 v8, v7, v6
	v_fma_f32 v9, -v5, v8, v7
	v_fmac_f32_e32 v8, v9, v6
	v_fma_f32 v5, -v5, v8, v7
	v_div_fmas_f32 v5, v5, v6, v8
	v_div_fixup_f32 v4, v5, v4, 1.0
	v_pk_mul_f32 v[80:81], v[4:5], v[80:81] op_sel_hi:[0,1]
	v_pk_mul_f32 v[82:83], v[4:5], v[82:83] op_sel_hi:[0,1]
	v_pk_mul_f32 v[84:85], v[4:5], v[84:85] op_sel_hi:[0,1]
	v_pk_mul_f32 v[86:87], v[4:5], v[86:87] op_sel_hi:[0,1]
	v_pk_mul_f32 v[88:89], v[4:5], v[88:89] op_sel_hi:[0,1]
	v_pk_mul_f32 v[90:91], v[4:5], v[90:91] op_sel_hi:[0,1]
	v_pk_mul_f32 v[92:93], v[4:5], v[92:93] op_sel_hi:[0,1]
	v_pk_mul_f32 v[94:95], v[4:5], v[94:95] op_sel_hi:[0,1]
	v_pk_mul_f32 v[80:81], v[80:81], v[96:97]
	v_pk_mul_f32 v[82:83], v[82:83], v[98:99]
	v_pk_mul_f32 v[84:85], v[84:85], v[100:101]
	v_pk_mul_f32 v[86:87], v[86:87], v[102:103]
	v_pk_mul_f32 v[88:89], v[88:89], v[104:105]
	v_pk_mul_f32 v[90:91], v[90:91], v[106:107]
	v_pk_mul_f32 v[92:93], v[92:93], v[108:109]
	v_pk_mul_f32 v[94:95], v[94:95], v[110:111]
	global_store_dwordx4 v19, v[80:83], s[6:7] offset:0 nt
	global_store_dwordx4 v19, v[84:87], s[6:7] offset:1024 nt
	global_store_dwordx4 v19, v[88:91], s[6:7] offset:2048 nt
	global_store_dwordx4 v19, v[92:95], s[6:7] offset:3072 nt
	v_add_u32_e32 v15, 0x2000000, v0
	global_load_dwordx4 v[80:83], v15, s[6:7] offset:0
	global_load_dwordx4 v[84:87], v15, s[6:7] offset:1024
	global_load_dwordx4 v[88:91], v15, s[6:7] offset:2048
	global_load_dwordx4 v[92:95], v15, s[6:7] offset:3072
	s_waitcnt vmcnt(24)
	v_pk_mul_f32 v[2:3], v[32:33], v[32:33]
	v_pk_fma_f32 v[2:3], v[34:35], v[34:35], v[2:3]
	v_pk_fma_f32 v[2:3], v[36:37], v[36:37], v[2:3]
	v_pk_fma_f32 v[2:3], v[38:39], v[38:39], v[2:3]
	v_pk_fma_f32 v[2:3], v[40:41], v[40:41], v[2:3]
	v_pk_fma_f32 v[2:3], v[42:43], v[42:43], v[2:3]
	v_pk_fma_f32 v[2:3], v[44:45], v[44:45], v[2:3]
	v_pk_fma_f32 v[2:3], v[46:47], v[46:47], v[2:3]
	v_add_f32_e32 v2, v2, v3
	s_nop 1
	v_add_f32_dpp v2, v2, v2 quad_perm:[1,0,3,2] row_mask:0xf bank_mask:0xf
	s_nop 1
	v_add_f32_dpp v2, v2, v2 quad_perm:[2,3,0,1] row_mask:0xf bank_mask:0xf
	s_nop 1
	v_add_f32_dpp v2, v2, v2 row_half_mirror row_mask:0xf bank_mask:0xf
	s_nop 1
	v_add_f32_dpp v2, v2, v2 row_mirror row_mask:0xf bank_mask:0xf
	s_nop 1
	v_readlane_b32 s20, v2, 0
	v_readlane_b32 s21, v2, 16
	v_readlane_b32 s22, v2, 32
	v_readlane_b32 s23, v2, 48
	s_nop 1
	v_mov_b32_e32 v4, s20
	v_add_f32_e32 v4, s21, v4
	v_add_f32_e32 v4, s22, v4
	v_add_f32_e32 v4, s23, v4
	v_fmamk_f32 v4, v4, 0x3a800000, v20
	v_mul_f32_e32 v5, 0x4f800000, v4
	v_cmp_gt_f32_e32 vcc, s19, v4
	s_nop 1
	v_cndmask_b32_e32 v4, v4, v5, vcc
	v_sqrt_f32_e32 v5, v4
	s_nop 0
	v_add_u32_e32 v6, -1, v5
	v_add_u32_e32 v7, 1, v5
	v_fma_f32 v8, -v6, v5, v4
	v_fma_f32 v9, -v7, v5, v4
	v_cmp_ge_f32_e64 s[0:1], 0, v8
	s_nop 1
	v_cndmask_b32_e64 v5, v5, v6, s[0:1]
	v_cmp_lt_f32_e64 s[0:1], 0, v9
	s_nop 1
	v_cndmask_b32_e64 v5, v5, v7, s[0:1]
	v_mul_f32_e32 v6, 0x37800000, v5
	v_cndmask_b32_e32 v5, v5, v6, vcc
	v_cmp_class_f32_e32 vcc, v4, v21
	s_nop 1
	v_cndmask_b32_e32 v4, v5, v4, vcc
	v_div_scale_f32 v5, s[0:1], v4, v4, 1.0
	v_rcp_f32_e32 v6, v5
	v_div_scale_f32 v7, vcc, 1.0, v4, 1.0
	v_fma_f32 v8, -v5, v6, 1.0
	v_fmac_f32_e32 v6, v8, v6
	v_mul_f32_e32 v8, v7, v6
	v_fma_f32 v9, -v5, v8, v7
	v_fmac_f32_e32 v8, v9, v6
	v_fma_f32 v5, -v5, v8, v7
	v_div_fmas_f32 v5, v5, v6, v8
	v_div_fixup_f32 v4, v5, v4, 1.0
	v_pk_mul_f32 v[32:33], v[4:5], v[32:33] op_sel_hi:[0,1]
	v_pk_mul_f32 v[34:35], v[4:5], v[34:35] op_sel_hi:[0,1]
	v_pk_mul_f32 v[36:37], v[4:5], v[36:37] op_sel_hi:[0,1]
	v_pk_mul_f32 v[38:39], v[4:5], v[38:39] op_sel_hi:[0,1]
	v_pk_mul_f32 v[40:41], v[4:5], v[40:41] op_sel_hi:[0,1]
	v_pk_mul_f32 v[42:43], v[4:5], v[42:43] op_sel_hi:[0,1]
	v_pk_mul_f32 v[44:45], v[4:5], v[44:45] op_sel_hi:[0,1]
	v_pk_mul_f32 v[46:47], v[4:5], v[46:47] op_sel_hi:[0,1]
	v_pk_mul_f32 v[32:33], v[32:33], v[96:97]
	v_pk_mul_f32 v[34:35], v[34:35], v[98:99]
	v_pk_mul_f32 v[36:37], v[36:37], v[100:101]
	v_pk_mul_f32 v[38:39], v[38:39], v[102:103]
	v_pk_mul_f32 v[40:41], v[40:41], v[104:105]
	v_pk_mul_f32 v[42:43], v[42:43], v[106:107]
	v_pk_mul_f32 v[44:45], v[44:45], v[108:109]
	v_pk_mul_f32 v[46:47], v[46:47], v[110:111]
	global_store_dwordx4 v12, v[32:35], s[6:7] offset:0 nt
	global_store_dwordx4 v12, v[36:39], s[6:7] offset:1024 nt
	global_store_dwordx4 v12, v[40:43], s[6:7] offset:2048 nt
	global_store_dwordx4 v12, v[44:47], s[6:7] offset:3072 nt
	v_add_u32_e32 v16, 0x1800000, v0
	global_load_dwordx4 v[32:35], v16, s[6:7] offset:0
	global_load_dwordx4 v[36:39], v16, s[6:7] offset:1024
	global_load_dwordx4 v[40:43], v16, s[6:7] offset:2048
	global_load_dwordx4 v[44:47], v16, s[6:7] offset:3072
	s_waitcnt vmcnt(24)
; #define ws (karg_ws())
; __global__ void __launch_bounds__(512, 2) fwd_megakernel(Args a) {
;     ...
;             for (int j = 0; j < 4; ++j) v[j] = __builtin_nontemporal_load(&yr[64 * j]);
;         } else {
; #pragma unroll
;             for (int j = 0; j < 4; ++j) { const u32x2 w = ((const u32x2*)(X1B + (size_t)r * DM))[lane + 64 * j]; v[j] = (f32x4){bflo(w.x), bfhi(w.x), bflo(w.y), bfhi(w.y)}; }
;         }
;         if (r >= MP) {
;             for (int ks = 0; ks < 11; ++ks) { const f32x4* pr = (const f32x4*)((float*)(ws + WS_PART) + ((size_t)ks * MS + (r - MP)) * DM) + lane;
; #pragma unroll
;                 for (int j = 0; j < 4; ++j) v[j] = v[j] + pr[64 * j]; } }
; #pragma unroll
;         for (int j = 0; j < 4; ++j) s += (v[j][0] * v[j][0] + v[j][1] * v[j][1]) + (v[j][2] * v[j][2] + v[j][3] * v[j][3]);
;         const float rs = 1.0f / sqrtf(wave_sum(s) * (1.0f / DM) + EPS);
; #pragma unroll
;         for (int j = 0; j < 4; ++j) { const f32x4 gv = ((const f32x4*)final_norm_g)[lane + 64 * j]; __builtin_nontemporal_store(v[j] * rs * gv, &yr[64 * j]); }
	v_pk_mul_f32 v[2:3], v[48:49], v[48:49]
	v_pk_fma_f32 v[2:3], v[50:51], v[50:51], v[2:3]
	v_pk_fma_f32 v[2:3], v[52:53], v[52:53], v[2:3]
	v_pk_fma_f32 v[2:3], v[54:55], v[54:55], v[2:3]
	v_pk_fma_f32 v[2:3], v[56:57], v[56:57], v[2:3]
	v_pk_fma_f32 v[2:3], v[58:59], v[58:59], v[2:3]
	v_pk_fma_f32 v[2:3], v[60:61], v[60:61], v[2:3]
	v_pk_fma_f32 v[2:3], v[62:63], v[62:63], v[2:3]
	v_add_f32_e32 v2, v2, v3
	s_nop 1
	v_add_f32_dpp v2, v2, v2 quad_perm:[1,0,3,2] row_mask:0xf bank_mask:0xf
	s_nop 1
	v_add_f32_dpp v2, v2, v2 quad_perm:[2,3,0,1] row_mask:0xf bank_mask:0xf
	s_nop 1
	v_add_f32_dpp v2, v2, v2 row_half_mirror row_mask:0xf bank_mask:0xf
	s_nop 1
	v_add_f32_dpp v2, v2, v2 row_mirror row_mask:0xf bank_mask:0xf
	s_nop 1
	v_readlane_b32 s20, v2, 0
	v_readlane_b32 s21, v2, 16
	v_readlane_b32 s22, v2, 32
	v_readlane_b32 s23, v2, 48
	s_nop 1
	v_mov_b32_e32 v4, s20
	v_add_f32_e32 v4, s21, v4
	v_add_f32_e32 v4, s22, v4
	v_add_f32_e32 v4, s23, v4
	v_fmamk_f32 v4, v4, 0x3a800000, v20
	v_mul_f32_e32 v5, 0x4f800000, v4
	v_cmp_gt_f32_e32 vcc, s19, v4
	s_nop 1
	v_cndmask_b32_e32 v4, v4, v5, vcc
	v_sqrt_f32_e32 v5, v4
	s_nop 0
	v_add_u32_e32 v6, -1, v5
	v_add_u32_e32 v7, 1, v5
	v_fma_f32 v8, -v6, v5, v4
	v_fma_f32 v9, -v7, v5, v4
	v_cmp_ge_f32_e64 s[0:1], 0, v8
	s_nop 1
	v_cndmask_b32_e64 v5, v5, v6, s[0:1]
	v_cmp_lt_f32_e64 s[0:1], 0, v9
	s_nop 1
	v_cndmask_b32_e64 v5, v5, v7, s[0:1]
	v_mul_f32_e32 v6, 0x37800000, v5
	v_cndmask_b32_e32 v5, v5, v6, vcc
	v_cmp_class_f32_e32 vcc, v4, v21
	s_nop 1
	v_cndmask_b32_e32 v4, v5, v4, vcc
	v_div_scale_f32 v5, s[0:1], v4, v4, 1.0
	v_rcp_f32_e32 v6, v5
	v_div_scale_f32 v7, vcc, 1.0, v4, 1.0
	v_fma_f32 v8, -v5, v6, 1.0
	v_fmac_f32_e32 v6, v8, v6
	v_mul_f32_e32 v8, v7, v6
	v_fma_f32 v9, -v5, v8, v7
	v_fmac_f32_e32 v8, v9, v6
	v_fma_f32 v5, -v5, v8, v7
	v_div_fmas_f32 v5, v5, v6, v8
	v_div_fixup_f32 v4, v5, v4, 1.0
	v_pk_mul_f32 v[48:49], v[4:5], v[48:49] op_sel_hi:[0,1]
	v_pk_mul_f32 v[50:51], v[4:5], v[50:51] op_sel_hi:[0,1]
	v_pk_mul_f32 v[52:53], v[4:5], v[52:53] op_sel_hi:[0,1]
	v_pk_mul_f32 v[54:55], v[4:5], v[54:55] op_sel_hi:[0,1]
	v_pk_mul_f32 v[56:57], v[4:5], v[56:57] op_sel_hi:[0,1]
	v_pk_mul_f32 v[58:59], v[4:5], v[58:59] op_sel_hi:[0,1]
	v_pk_mul_f32 v[60:61], v[4:5], v[60:61] op_sel_hi:[0,1]
	v_pk_mul_f32 v[62:63], v[4:5], v[62:63] op_sel_hi:[0,1]
	v_pk_mul_f32 v[48:49], v[48:49], v[96:97]
	v_pk_mul_f32 v[50:51], v[50:51], v[98:99]
	v_pk_mul_f32 v[52:53], v[52:53], v[100:101]
	v_pk_mul_f32 v[54:55], v[54:55], v[102:103]
	v_pk_mul_f32 v[56:57], v[56:57], v[104:105]
	v_pk_mul_f32 v[58:59], v[58:59], v[106:107]
	v_pk_mul_f32 v[60:61], v[60:61], v[108:109]
	v_pk_mul_f32 v[62:63], v[62:63], v[110:111]
	global_store_dwordx4 v13, v[48:51], s[6:7] offset:0 nt
	global_store_dwordx4 v13, v[52:55], s[6:7] offset:1024 nt
	global_store_dwordx4 v13, v[56:59], s[6:7] offset:2048 nt
	global_store_dwordx4 v13, v[60:63], s[6:7] offset:3072 nt
	v_add_u32_e32 v17, 0x1000000, v0
	global_load_dwordx4 v[48:51], v17, s[6:7] offset:0
	global_load_dwordx4 v[52:55], v17, s[6:7] offset:1024
	global_load_dwordx4 v[56:59], v17, s[6:7] offset:2048
	global_load_dwordx4 v[60:63], v17, s[6:7] offset:3072
	s_waitcnt vmcnt(24)
	v_pk_mul_f32 v[2:3], v[64:65], v[64:65]
	v_pk_fma_f32 v[2:3], v[66:67], v[66:67], v[2:3]
	v_pk_fma_f32 v[2:3], v[68:69], v[68:69], v[2:3]
	v_pk_fma_f32 v[2:3], v[70:71], v[70:71], v[2:3]
	v_pk_fma_f32 v[2:3], v[72:73], v[72:73], v[2:3]
	v_pk_fma_f32 v[2:3], v[74:75], v[74:75], v[2:3]
	v_pk_fma_f32 v[2:3], v[76:77], v[76:77], v[2:3]
	v_pk_fma_f32 v[2:3], v[78:79], v[78:79], v[2:3]
	v_add_f32_e32 v2, v2, v3
	s_nop 1
	v_add_f32_dpp v2, v2, v2 quad_perm:[1,0,3,2] row_mask:0xf bank_mask:0xf
	s_nop 1
	v_add_f32_dpp v2, v2, v2 quad_perm:[2,3,0,1] row_mask:0xf bank_mask:0xf
	s_nop 1
	v_add_f32_dpp v2, v2, v2 row_half_mirror row_mask:0xf bank_mask:0xf
	s_nop 1
	v_add_f32_dpp v2, v2, v2 row_mirror row_mask:0xf bank_mask:0xf
	s_nop 1
	v_readlane_b32 s20, v2, 0
	v_readlane_b32 s21, v2, 16
	v_readlane_b32 s22, v2, 32
	v_readlane_b32 s23, v2, 48
	s_nop 1
	v_mov_b32_e32 v4, s20
	v_add_f32_e32 v4, s21, v4
	v_add_f32_e32 v4, s22, v4
	v_add_f32_e32 v4, s23, v4
	v_fmamk_f32 v4, v4, 0x3a800000, v20
	v_mul_f32_e32 v5, 0x4f800000, v4
	v_cmp_gt_f32_e32 vcc, s19, v4
	s_nop 1
	v_cndmask_b32_e32 v4, v4, v5, vcc
	v_sqrt_f32_e32 v5, v4
	s_nop 0
	v_add_u32_e32 v6, -1, v5
	v_add_u32_e32 v7, 1, v5
	v_fma_f32 v8, -v6, v5, v4
	v_fma_f32 v9, -v7, v5, v4
	v_cmp_ge_f32_e64 s[0:1], 0, v8
	s_nop 1
	v_cndmask_b32_e64 v5, v5, v6, s[0:1]
	v_cmp_lt_f32_e64 s[0:1], 0, v9
	s_nop 1
	v_cndmask_b32_e64 v5, v5, v7, s[0:1]
	v_mul_f32_e32 v6, 0x37800000, v5
	v_cndmask_b32_e32 v5, v5, v6, vcc
	v_cmp_class_f32_e32 vcc, v4, v21
	s_nop 1
	v_cndmask_b32_e32 v4, v5, v4, vcc
	v_div_scale_f32 v5, s[0:1], v4, v4, 1.0
	v_rcp_f32_e32 v6, v5
	v_div_scale_f32 v7, vcc, 1.0, v4, 1.0
	v_fma_f32 v8, -v5, v6, 1.0
	v_fmac_f32_e32 v6, v8, v6
	v_mul_f32_e32 v8, v7, v6
	v_fma_f32 v9, -v5, v8, v7
	v_fmac_f32_e32 v8, v9, v6
	v_fma_f32 v5, -v5, v8, v7
	v_div_fmas_f32 v5, v5, v6, v8
	v_div_fixup_f32 v4, v5, v4, 1.0
	v_pk_mul_f32 v[64:65], v[4:5], v[64:65] op_sel_hi:[0,1]
	v_pk_mul_f32 v[66:67], v[4:5], v[66:67] op_sel_hi:[0,1]
	v_pk_mul_f32 v[68:69], v[4:5], v[68:69] op_sel_hi:[0,1]
	v_pk_mul_f32 v[70:71], v[4:5], v[70:71] op_sel_hi:[0,1]
	v_pk_mul_f32 v[72:73], v[4:5], v[72:73] op_sel_hi:[0,1]
	v_pk_mul_f32 v[74:75], v[4:5], v[74:75] op_sel_hi:[0,1]
	v_pk_mul_f32 v[76:77], v[4:5], v[76:77] op_sel_hi:[0,1]
	v_pk_mul_f32 v[78:79], v[4:5], v[78:79] op_sel_hi:[0,1]
	v_pk_mul_f32 v[64:65], v[64:65], v[96:97]
	v_pk_mul_f32 v[66:67], v[66:67], v[98:99]
	v_pk_mul_f32 v[68:69], v[68:69], v[100:101]
	v_pk_mul_f32 v[70:71], v[70:71], v[102:103]
	v_pk_mul_f32 v[72:73], v[72:73], v[104:105]
	v_pk_mul_f32 v[74:75], v[74:75], v[106:107]
	v_pk_mul_f32 v[76:77], v[76:77], v[108:109]
	v_pk_mul_f32 v[78:79], v[78:79], v[110:111]
	global_store_dwordx4 v14, v[64:67], s[6:7] offset:0 nt
	global_store_dwordx4 v14, v[68:71], s[6:7] offset:1024 nt
	global_store_dwordx4 v14, v[72:75], s[6:7] offset:2048 nt
	global_store_dwordx4 v14, v[76:79], s[6:7] offset:3072 nt
	v_add_u32_e32 v18, 0x800000, v0
	global_load_dwordx4 v[64:67], v18, s[6:7] offset:0
	global_load_dwordx4 v[68:71], v18, s[6:7] offset:1024
	global_load_dwordx4 v[72:75], v18, s[6:7] offset:2048
	global_load_dwordx4 v[76:79], v18, s[6:7] offset:3072
	s_waitcnt vmcnt(24)
; #define ws (karg_ws())
; __global__ void __launch_bounds__(512, 2) fwd_megakernel(Args a) {
;     ...
;             for (int j = 0; j < 4; ++j) v[j] = __builtin_nontemporal_load(&yr[64 * j]);
;         } else {
; #pragma unroll
;             for (int j = 0; j < 4; ++j) { const u32x2 w = ((const u32x2*)(X1B + (size_t)r * DM))[lane + 64 * j]; v[j] = (f32x4){bflo(w.x), bfhi(w.x), bflo(w.y), bfhi(w.y)}; }
;         }
;         if (r >= MP) {
;             for (int ks = 0; ks < 11; ++ks) { const f32x4* pr = (const f32x4*)((float*)(ws + WS_PART) + ((size_t)ks * MS + (r - MP)) * DM) + lane;
; #pragma unroll
;                 for (int j = 0; j < 4; ++j) v[j] = v[j] + pr[64 * j]; } }
; #pragma unroll
;         for (int j = 0; j < 4; ++j) s += (v[j][0] * v[j][0] + v[j][1] * v[j][1]) + (v[j][2] * v[j][2] + v[j][3] * v[j][3]);
;         const float rs = 1.0f / sqrtf(wave_sum(s) * (1.0f / DM) + EPS);
; #pragma unroll
;         for (int j = 0; j < 4; ++j) { const f32x4 gv = ((const f32x4*)final_norm_g)[lane + 64 * j]; __builtin_nontemporal_store(v[j] * rs * gv, &yr[64 * j]); }
	v_pk_mul_f32 v[2:3], v[80:81], v[80:81]
	v_pk_fma_f32 v[2:3], v[82:83], v[82:83], v[2:3]
	v_pk_fma_f32 v[2:3], v[84:85], v[84:85], v[2:3]
	v_pk_fma_f32 v[2:3], v[86:87], v[86:87], v[2:3]
	v_pk_fma_f32 v[2:3], v[88:89], v[88:89], v[2:3]
	v_pk_fma_f32 v[2:3], v[90:91], v[90:91], v[2:3]
	v_pk_fma_f32 v[2:3], v[92:93], v[92:93], v[2:3]
	v_pk_fma_f32 v[2:3], v[94:95], v[94:95], v[2:3]
	v_add_f32_e32 v2, v2, v3
	s_nop 1
	v_add_f32_dpp v2, v2, v2 quad_perm:[1,0,3,2] row_mask:0xf bank_mask:0xf
	s_nop 1
	v_add_f32_dpp v2, v2, v2 quad_perm:[2,3,0,1] row_mask:0xf bank_mask:0xf
	s_nop 1
	v_add_f32_dpp v2, v2, v2 row_half_mirror row_mask:0xf bank_mask:0xf
	s_nop 1
	v_add_f32_dpp v2, v2, v2 row_mirror row_mask:0xf bank_mask:0xf
	s_nop 1
	v_readlane_b32 s20, v2, 0
	v_readlane_b32 s21, v2, 16
	v_readlane_b32 s22, v2, 32
	v_readlane_b32 s23, v2, 48
	s_nop 1
	v_mov_b32_e32 v4, s20
	v_add_f32_e32 v4, s21, v4
	v_add_f32_e32 v4, s22, v4
	v_add_f32_e32 v4, s23, v4
	v_fmamk_f32 v4, v4, 0x3a800000, v20
	v_mul_f32_e32 v5, 0x4f800000, v4
	v_cmp_gt_f32_e32 vcc, s19, v4
	s_nop 1
	v_cndmask_b32_e32 v4, v4, v5, vcc
	v_sqrt_f32_e32 v5, v4
	s_nop 0
	v_add_u32_e32 v6, -1, v5
	v_add_u32_e32 v7, 1, v5
	v_fma_f32 v8, -v6, v5, v4
	v_fma_f32 v9, -v7, v5, v4
	v_cmp_ge_f32_e64 s[0:1], 0, v8
	s_nop 1
	v_cndmask_b32_e64 v5, v5, v6, s[0:1]
	v_cmp_lt_f32_e64 s[0:1], 0, v9
	s_nop 1
	v_cndmask_b32_e64 v5, v5, v7, s[0:1]
	v_mul_f32_e32 v6, 0x37800000, v5
	v_cndmask_b32_e32 v5, v5, v6, vcc
	v_cmp_class_f32_e32 vcc, v4, v21
	s_nop 1
	v_cndmask_b32_e32 v4, v5, v4, vcc
	v_div_scale_f32 v5, s[0:1], v4, v4, 1.0
	v_rcp_f32_e32 v6, v5
	v_div_scale_f32 v7, vcc, 1.0, v4, 1.0
	v_fma_f32 v8, -v5, v6, 1.0
	v_fmac_f32_e32 v6, v8, v6
	v_mul_f32_e32 v8, v7, v6
	v_fma_f32 v9, -v5, v8, v7
	v_fmac_f32_e32 v8, v9, v6
	v_fma_f32 v5, -v5, v8, v7
	v_div_fmas_f32 v5, v5, v6, v8
	v_div_fixup_f32 v4, v5, v4, 1.0
	v_pk_mul_f32 v[80:81], v[4:5], v[80:81] op_sel_hi:[0,1]
	v_pk_mul_f32 v[82:83], v[4:5], v[82:83] op_sel_hi:[0,1]
	v_pk_mul_f32 v[84:85], v[4:5], v[84:85] op_sel_hi:[0,1]
	v_pk_mul_f32 v[86:87], v[4:5], v[86:87] op_sel_hi:[0,1]
	v_pk_mul_f32 v[88:89], v[4:5], v[88:89] op_sel_hi:[0,1]
	v_pk_mul_f32 v[90:91], v[4:5], v[90:91] op_sel_hi:[0,1]
	v_pk_mul_f32 v[92:93], v[4:5], v[92:93] op_sel_hi:[0,1]
	v_pk_mul_f32 v[94:95], v[4:5], v[94:95] op_sel_hi:[0,1]
	v_pk_mul_f32 v[80:81], v[80:81], v[96:97]
	v_pk_mul_f32 v[82:83], v[82:83], v[98:99]
	v_pk_mul_f32 v[84:85], v[84:85], v[100:101]
	v_pk_mul_f32 v[86:87], v[86:87], v[102:103]
	v_pk_mul_f32 v[88:89], v[88:89], v[104:105]
	v_pk_mul_f32 v[90:91], v[90:91], v[106:107]
	v_pk_mul_f32 v[92:93], v[92:93], v[108:109]
	v_pk_mul_f32 v[94:95], v[94:95], v[110:111]
	global_store_dwordx4 v15, v[80:83], s[6:7] offset:0 nt
	global_store_dwordx4 v15, v[84:87], s[6:7] offset:1024 nt
	global_store_dwordx4 v15, v[88:91], s[6:7] offset:2048 nt
	global_store_dwordx4 v15, v[92:95], s[6:7] offset:3072 nt
	v_mov_b32_e32 v19, v0
	global_load_dwordx4 v[80:83], v19, s[6:7] offset:0
	global_load_dwordx4 v[84:87], v19, s[6:7] offset:1024
	global_load_dwordx4 v[88:91], v19, s[6:7] offset:2048
	global_load_dwordx4 v[92:95], v19, s[6:7] offset:3072
	s_waitcnt vmcnt(24)
	v_pk_mul_f32 v[2:3], v[32:33], v[32:33]
	v_pk_fma_f32 v[2:3], v[34:35], v[34:35], v[2:3]
	v_pk_fma_f32 v[2:3], v[36:37], v[36:37], v[2:3]
	v_pk_fma_f32 v[2:3], v[38:39], v[38:39], v[2:3]
	v_pk_fma_f32 v[2:3], v[40:41], v[40:41], v[2:3]
	v_pk_fma_f32 v[2:3], v[42:43], v[42:43], v[2:3]
	v_pk_fma_f32 v[2:3], v[44:45], v[44:45], v[2:3]
	v_pk_fma_f32 v[2:3], v[46:47], v[46:47], v[2:3]
	v_add_f32_e32 v2, v2, v3
	s_nop 1
	v_add_f32_dpp v2, v2, v2 quad_perm:[1,0,3,2] row_mask:0xf bank_mask:0xf
	s_nop 1
	v_add_f32_dpp v2, v2, v2 quad_perm:[2,3,0,1] row_mask:0xf bank_mask:0xf
	s_nop 1
	v_add_f32_dpp v2, v2, v2 row_half_mirror row_mask:0xf bank_mask:0xf
	s_nop 1
	v_add_f32_dpp v2, v2, v2 row_mirror row_mask:0xf bank_mask:0xf
	s_nop 1
	v_readlane_b32 s20, v2, 0
	v_readlane_b32 s21, v2, 16
	v_readlane_b32 s22, v2, 32
	v_readlane_b32 s23, v2, 48
	s_nop 1
	v_mov_b32_e32 v4, s20
	v_add_f32_e32 v4, s21, v4
	v_add_f32_e32 v4, s22, v4
	v_add_f32_e32 v4, s23, v4
	v_fmamk_f32 v4, v4, 0x3a800000, v20
	v_mul_f32_e32 v5, 0x4f800000, v4
	v_cmp_gt_f32_e32 vcc, s19, v4
	s_nop 1
	v_cndmask_b32_e32 v4, v4, v5, vcc
	v_sqrt_f32_e32 v5, v4
	s_nop 0
	v_add_u32_e32 v6, -1, v5
	v_add_u32_e32 v7, 1, v5
	v_fma_f32 v8, -v6, v5, v4
	v_fma_f32 v9, -v7, v5, v4
	v_cmp_ge_f32_e64 s[0:1], 0, v8
	s_nop 1
	v_cndmask_b32_e64 v5, v5, v6, s[0:1]
	v_cmp_lt_f32_e64 s[0:1], 0, v9
	s_nop 1
	v_cndmask_b32_e64 v5, v5, v7, s[0:1]
	v_mul_f32_e32 v6, 0x37800000, v5
	v_cndmask_b32_e32 v5, v5, v6, vcc
	v_cmp_class_f32_e32 vcc, v4, v21
	s_nop 1
	v_cndmask_b32_e32 v4, v5, v4, vcc
	v_div_scale_f32 v5, s[0:1], v4, v4, 1.0
	v_rcp_f32_e32 v6, v5
	v_div_scale_f32 v7, vcc, 1.0, v4, 1.0
	v_fma_f32 v8, -v5, v6, 1.0
	v_fmac_f32_e32 v6, v8, v6
	v_mul_f32_e32 v8, v7, v6
	v_fma_f32 v9, -v5, v8, v7
	v_fmac_f32_e32 v8, v9, v6
	v_fma_f32 v5, -v5, v8, v7
	v_div_fmas_f32 v5, v5, v6, v8
	v_div_fixup_f32 v4, v5, v4, 1.0
	v_pk_mul_f32 v[32:33], v[4:5], v[32:33] op_sel_hi:[0,1]
	v_pk_mul_f32 v[34:35], v[4:5], v[34:35] op_sel_hi:[0,1]
	v_pk_mul_f32 v[36:37], v[4:5], v[36:37] op_sel_hi:[0,1]
	v_pk_mul_f32 v[38:39], v[4:5], v[38:39] op_sel_hi:[0,1]
	v_pk_mul_f32 v[40:41], v[4:5], v[40:41] op_sel_hi:[0,1]
	v_pk_mul_f32 v[42:43], v[4:5], v[42:43] op_sel_hi:[0,1]
	v_pk_mul_f32 v[44:45], v[4:5], v[44:45] op_sel_hi:[0,1]
	v_pk_mul_f32 v[46:47], v[4:5], v[46:47] op_sel_hi:[0,1]
	v_pk_mul_f32 v[32:33], v[32:33], v[96:97]
	v_pk_mul_f32 v[34:35], v[34:35], v[98:99]
	v_pk_mul_f32 v[36:37], v[36:37], v[100:101]
	v_pk_mul_f32 v[38:39], v[38:39], v[102:103]
	v_pk_mul_f32 v[40:41], v[40:41], v[104:105]
	v_pk_mul_f32 v[42:43], v[42:43], v[106:107]
	v_pk_mul_f32 v[44:45], v[44:45], v[108:109]
	v_pk_mul_f32 v[46:47], v[46:47], v[110:111]
	global_store_dwordx4 v16, v[32:35], s[6:7] offset:0 nt
	global_store_dwordx4 v16, v[36:39], s[6:7] offset:1024 nt
	global_store_dwordx4 v16, v[40:43], s[6:7] offset:2048 nt
	global_store_dwordx4 v16, v[44:47], s[6:7] offset:3072 nt
	s_waitcnt vmcnt(20)
; __global__ void __launch_bounds__(512, 2) fwd_megakernel(Args a) {
;     ...
; #pragma unroll
;         for (int j = 0; j < 4; ++j) s += (v[j][0] * v[j][0] + v[j][1] * v[j][1]) + (v[j][2] * v[j][2] + v[j][3] * v[j][3]);
;         const float rs = 1.0f / sqrtf(wave_sum(s) * (1.0f / DM) + EPS);
; #pragma unroll
;         for (int j = 0; j < 4; ++j) { const f32x4 gv = ((const f32x4*)final_norm_g)[lane + 64 * j]; __builtin_nontemporal_store(v[j] * rs * gv, &yr[64 * j]); }
	v_pk_mul_f32 v[2:3], v[48:49], v[48:49]
	v_pk_fma_f32 v[2:3], v[50:51], v[50:51], v[2:3]
	v_pk_fma_f32 v[2:3], v[52:53], v[52:53], v[2:3]
	v_pk_fma_f32 v[2:3], v[54:55], v[54:55], v[2:3]
	v_pk_fma_f32 v[2:3], v[56:57], v[56:57], v[2:3]
	v_pk_fma_f32 v[2:3], v[58:59], v[58:59], v[2:3]
	v_pk_fma_f32 v[2:3], v[60:61], v[60:61], v[2:3]
	v_pk_fma_f32 v[2:3], v[62:63], v[62:63], v[2:3]
	v_add_f32_e32 v2, v2, v3
	s_nop 1
	v_add_f32_dpp v2, v2, v2 quad_perm:[1,0,3,2] row_mask:0xf bank_mask:0xf
	s_nop 1
	v_add_f32_dpp v2, v2, v2 quad_perm:[2,3,0,1] row_mask:0xf bank_mask:0xf
	s_nop 1
	v_add_f32_dpp v2, v2, v2 row_half_mirror row_mask:0xf bank_mask:0xf
	s_nop 1
	v_add_f32_dpp v2, v2, v2 row_mirror row_mask:0xf bank_mask:0xf
	s_nop 1
	v_readlane_b32 s20, v2, 0
	v_readlane_b32 s21, v2, 16
	v_readlane_b32 s22, v2, 32
	v_readlane_b32 s23, v2, 48
	s_nop 1
	v_mov_b32_e32 v4, s20
	v_add_f32_e32 v4, s21, v4
	v_add_f32_e32 v4, s22, v4
	v_add_f32_e32 v4, s23, v4
	v_fmamk_f32 v4, v4, 0x3a800000, v20
	v_mul_f32_e32 v5, 0x4f800000, v4
	v_cmp_gt_f32_e32 vcc, s19, v4
	s_nop 1
	v_cndmask_b32_e32 v4, v4, v5, vcc
	v_sqrt_f32_e32 v5, v4
	s_nop 0
	v_add_u32_e32 v6, -1, v5
	v_add_u32_e32 v7, 1, v5
	v_fma_f32 v8, -v6, v5, v4
	v_fma_f32 v9, -v7, v5, v4
	v_cmp_ge_f32_e64 s[0:1], 0, v8
	s_nop 1
	v_cndmask_b32_e64 v5, v5, v6, s[0:1]
	v_cmp_lt_f32_e64 s[0:1], 0, v9
	s_nop 1
	v_cndmask_b32_e64 v5, v5, v7, s[0:1]
	v_mul_f32_e32 v6, 0x37800000, v5
	v_cndmask_b32_e32 v5, v5, v6, vcc
	v_cmp_class_f32_e32 vcc, v4, v21
	s_nop 1
	v_cndmask_b32_e32 v4, v5, v4, vcc
	v_div_scale_f32 v5, s[0:1], v4, v4, 1.0
	v_rcp_f32_e32 v6, v5
	v_div_scale_f32 v7, vcc, 1.0, v4, 1.0
	v_fma_f32 v8, -v5, v6, 1.0
	v_fmac_f32_e32 v6, v8, v6
	v_mul_f32_e32 v8, v7, v6
	v_fma_f32 v9, -v5, v8, v7
	v_fmac_f32_e32 v8, v9, v6
	v_fma_f32 v5, -v5, v8, v7
	v_div_fmas_f32 v5, v5, v6, v8
	v_div_fixup_f32 v4, v5, v4, 1.0
	v_pk_mul_f32 v[48:49], v[4:5], v[48:49] op_sel_hi:[0,1]
	v_pk_mul_f32 v[50:51], v[4:5], v[50:51] op_sel_hi:[0,1]
	v_pk_mul_f32 v[52:53], v[4:5], v[52:53] op_sel_hi:[0,1]
	v_pk_mul_f32 v[54:55], v[4:5], v[54:55] op_sel_hi:[0,1]
	v_pk_mul_f32 v[56:57], v[4:5], v[56:57] op_sel_hi:[0,1]
	v_pk_mul_f32 v[58:59], v[4:5], v[58:59] op_sel_hi:[0,1]
	v_pk_mul_f32 v[60:61], v[4:5], v[60:61] op_sel_hi:[0,1]
	v_pk_mul_f32 v[62:63], v[4:5], v[62:63] op_sel_hi:[0,1]
	v_pk_mul_f32 v[48:49], v[48:49], v[96:97]
	v_pk_mul_f32 v[50:51], v[50:51], v[98:99]
	v_pk_mul_f32 v[52:53], v[52:53], v[100:101]
	v_pk_mul_f32 v[54:55], v[54:55], v[102:103]
	v_pk_mul_f32 v[56:57], v[56:57], v[104:105]
	v_pk_mul_f32 v[58:59], v[58:59], v[106:107]
	v_pk_mul_f32 v[60:61], v[60:61], v[108:109]
	v_pk_mul_f32 v[62:63], v[62:63], v[110:111]
	global_store_dwordx4 v17, v[48:51], s[6:7] offset:0 nt
	global_store_dwordx4 v17, v[52:55], s[6:7] offset:1024 nt
	global_store_dwordx4 v17, v[56:59], s[6:7] offset:2048 nt
	global_store_dwordx4 v17, v[60:63], s[6:7] offset:3072 nt
	s_waitcnt vmcnt(16)
; __global__ void __launch_bounds__(512, 2) fwd_megakernel(Args a) {
;     ...
; #pragma unroll
;         for (int j = 0; j < 4; ++j) s += (v[j][0] * v[j][0] + v[j][1] * v[j][1]) + (v[j][2] * v[j][2] + v[j][3] * v[j][3]);
;         const float rs = 1.0f / sqrtf(wave_sum(s) * (1.0f / DM) + EPS);
; #pragma unroll
;         for (int j = 0; j < 4; ++j) { const f32x4 gv = ((const f32x4*)final_norm_g)[lane + 64 * j]; __builtin_nontemporal_store(v[j] * rs * gv, &yr[64 * j]); }
	v_pk_mul_f32 v[2:3], v[64:65], v[64:65]
	v_pk_fma_f32 v[2:3], v[66:67], v[66:67], v[2:3]
	v_pk_fma_f32 v[2:3], v[68:69], v[68:69], v[2:3]
	v_pk_fma_f32 v[2:3], v[70:71], v[70:71], v[2:3]
	v_pk_fma_f32 v[2:3], v[72:73], v[72:73], v[2:3]
	v_pk_fma_f32 v[2:3], v[74:75], v[74:75], v[2:3]
	v_pk_fma_f32 v[2:3], v[76:77], v[76:77], v[2:3]
	v_pk_fma_f32 v[2:3], v[78:79], v[78:79], v[2:3]
	v_add_f32_e32 v2, v2, v3
	s_nop 1
	v_add_f32_dpp v2, v2, v2 quad_perm:[1,0,3,2] row_mask:0xf bank_mask:0xf
	s_nop 1
	v_add_f32_dpp v2, v2, v2 quad_perm:[2,3,0,1] row_mask:0xf bank_mask:0xf
	s_nop 1
	v_add_f32_dpp v2, v2, v2 row_half_mirror row_mask:0xf bank_mask:0xf
	s_nop 1
	v_add_f32_dpp v2, v2, v2 row_mirror row_mask:0xf bank_mask:0xf
	s_nop 1
	v_readlane_b32 s20, v2, 0
	v_readlane_b32 s21, v2, 16
	v_readlane_b32 s22, v2, 32
	v_readlane_b32 s23, v2, 48
	s_nop 1
	v_mov_b32_e32 v4, s20
	v_add_f32_e32 v4, s21, v4
	v_add_f32_e32 v4, s22, v4
	v_add_f32_e32 v4, s23, v4
	v_fmamk_f32 v4, v4, 0x3a800000, v20
	v_mul_f32_e32 v5, 0x4f800000, v4
	v_cmp_gt_f32_e32 vcc, s19, v4
	s_nop 1
	v_cndmask_b32_e32 v4, v4, v5, vcc
	v_sqrt_f32_e32 v5, v4
	s_nop 0
	v_add_u32_e32 v6, -1, v5
	v_add_u32_e32 v7, 1, v5
	v_fma_f32 v8, -v6, v5, v4
	v_fma_f32 v9, -v7, v5, v4
	v_cmp_ge_f32_e64 s[0:1], 0, v8
	s_nop 1
	v_cndmask_b32_e64 v5, v5, v6, s[0:1]
	v_cmp_lt_f32_e64 s[0:1], 0, v9
	s_nop 1
	v_cndmask_b32_e64 v5, v5, v7, s[0:1]
	v_mul_f32_e32 v6, 0x37800000, v5
	v_cndmask_b32_e32 v5, v5, v6, vcc
	v_cmp_class_f32_e32 vcc, v4, v21
	s_nop 1
	v_cndmask_b32_e32 v4, v5, v4, vcc
	v_div_scale_f32 v5, s[0:1], v4, v4, 1.0
	v_rcp_f32_e32 v6, v5
	v_div_scale_f32 v7, vcc, 1.0, v4, 1.0
	v_fma_f32 v8, -v5, v6, 1.0
	v_fmac_f32_e32 v6, v8, v6
	v_mul_f32_e32 v8, v7, v6
	v_fma_f32 v9, -v5, v8, v7
	v_fmac_f32_e32 v8, v9, v6
	v_fma_f32 v5, -v5, v8, v7
	v_div_fmas_f32 v5, v5, v6, v8
	v_div_fixup_f32 v4, v5, v4, 1.0
	v_pk_mul_f32 v[64:65], v[4:5], v[64:65] op_sel_hi:[0,1]
	v_pk_mul_f32 v[66:67], v[4:5], v[66:67] op_sel_hi:[0,1]
	v_pk_mul_f32 v[68:69], v[4:5], v[68:69] op_sel_hi:[0,1]
	v_pk_mul_f32 v[70:71], v[4:5], v[70:71] op_sel_hi:[0,1]
	v_pk_mul_f32 v[72:73], v[4:5], v[72:73] op_sel_hi:[0,1]
	v_pk_mul_f32 v[74:75], v[4:5], v[74:75] op_sel_hi:[0,1]
	v_pk_mul_f32 v[76:77], v[4:5], v[76:77] op_sel_hi:[0,1]
	v_pk_mul_f32 v[78:79], v[4:5], v[78:79] op_sel_hi:[0,1]
	v_pk_mul_f32 v[64:65], v[64:65], v[96:97]
	v_pk_mul_f32 v[66:67], v[66:67], v[98:99]
	v_pk_mul_f32 v[68:69], v[68:69], v[100:101]
	v_pk_mul_f32 v[70:71], v[70:71], v[102:103]
	v_pk_mul_f32 v[72:73], v[72:73], v[104:105]
	v_pk_mul_f32 v[74:75], v[74:75], v[106:107]
	v_pk_mul_f32 v[76:77], v[76:77], v[108:109]
	v_pk_mul_f32 v[78:79], v[78:79], v[110:111]
	global_store_dwordx4 v18, v[64:67], s[6:7] offset:0 nt
	global_store_dwordx4 v18, v[68:71], s[6:7] offset:1024 nt
	global_store_dwordx4 v18, v[72:75], s[6:7] offset:2048 nt
	global_store_dwordx4 v18, v[76:79], s[6:7] offset:3072 nt
	s_waitcnt vmcnt(12)
	v_pk_mul_f32 v[2:3], v[80:81], v[80:81]
	v_pk_fma_f32 v[2:3], v[82:83], v[82:83], v[2:3]
	v_pk_fma_f32 v[2:3], v[84:85], v[84:85], v[2:3]
	v_pk_fma_f32 v[2:3], v[86:87], v[86:87], v[2:3]
	v_pk_fma_f32 v[2:3], v[88:89], v[88:89], v[2:3]
	v_pk_fma_f32 v[2:3], v[90:91], v[90:91], v[2:3]
	v_pk_fma_f32 v[2:3], v[92:93], v[92:93], v[2:3]
	v_pk_fma_f32 v[2:3], v[94:95], v[94:95], v[2:3]
	v_add_f32_e32 v2, v2, v3
	s_nop 1
	v_add_f32_dpp v2, v2, v2 quad_perm:[1,0,3,2] row_mask:0xf bank_mask:0xf
	s_nop 1
	v_add_f32_dpp v2, v2, v2 quad_perm:[2,3,0,1] row_mask:0xf bank_mask:0xf
	s_nop 1
	v_add_f32_dpp v2, v2, v2 row_half_mirror row_mask:0xf bank_mask:0xf
	s_nop 1
	v_add_f32_dpp v2, v2, v2 row_mirror row_mask:0xf bank_mask:0xf
	s_nop 1
	v_readlane_b32 s20, v2, 0
	v_readlane_b32 s21, v2, 16
	v_readlane_b32 s22, v2, 32
	v_readlane_b32 s23, v2, 48
	s_nop 1
	v_mov_b32_e32 v4, s20
	v_add_f32_e32 v4, s21, v4
	v_add_f32_e32 v4, s22, v4
	v_add_f32_e32 v4, s23, v4
	v_fmamk_f32 v4, v4, 0x3a800000, v20
	v_mul_f32_e32 v5, 0x4f800000, v4
	v_cmp_gt_f32_e32 vcc, s19, v4
	s_nop 1
	v_cndmask_b32_e32 v4, v4, v5, vcc
	v_sqrt_f32_e32 v5, v4
	s_nop 0
	v_add_u32_e32 v6, -1, v5
	v_add_u32_e32 v7, 1, v5
	v_fma_f32 v8, -v6, v5, v4
	v_fma_f32 v9, -v7, v5, v4
	v_cmp_ge_f32_e64 s[0:1], 0, v8
	s_nop 1
	v_cndmask_b32_e64 v5, v5, v6, s[0:1]
	v_cmp_lt_f32_e64 s[0:1], 0, v9
	s_nop 1
	v_cndmask_b32_e64 v5, v5, v7, s[0:1]
	v_mul_f32_e32 v6, 0x37800000, v5
	v_cndmask_b32_e32 v5, v5, v6, vcc
	v_cmp_class_f32_e32 vcc, v4, v21
	s_nop 1
	v_cndmask_b32_e32 v4, v5, v4, vcc
	v_div_scale_f32 v5, s[0:1], v4, v4, 1.0
	v_rcp_f32_e32 v6, v5
	v_div_scale_f32 v7, vcc, 1.0, v4, 1.0
	v_fma_f32 v8, -v5, v6, 1.0
	v_fmac_f32_e32 v6, v8, v6
	v_mul_f32_e32 v8, v7, v6
	v_fma_f32 v9, -v5, v8, v7
	v_fmac_f32_e32 v8, v9, v6
	v_fma_f32 v5, -v5, v8, v7
	v_div_fmas_f32 v5, v5, v6, v8
	v_div_fixup_f32 v4, v5, v4, 1.0
	v_pk_mul_f32 v[80:81], v[4:5], v[80:81] op_sel_hi:[0,1]
	v_pk_mul_f32 v[82:83], v[4:5], v[82:83] op_sel_hi:[0,1]
	v_pk_mul_f32 v[84:85], v[4:5], v[84:85] op_sel_hi:[0,1]
	v_pk_mul_f32 v[86:87], v[4:5], v[86:87] op_sel_hi:[0,1]
	v_pk_mul_f32 v[88:89], v[4:5], v[88:89] op_sel_hi:[0,1]
	v_pk_mul_f32 v[90:91], v[4:5], v[90:91] op_sel_hi:[0,1]
	v_pk_mul_f32 v[92:93], v[4:5], v[92:93] op_sel_hi:[0,1]
	v_pk_mul_f32 v[94:95], v[4:5], v[94:95] op_sel_hi:[0,1]
	v_pk_mul_f32 v[80:81], v[80:81], v[96:97]
	v_pk_mul_f32 v[82:83], v[82:83], v[98:99]
	v_pk_mul_f32 v[84:85], v[84:85], v[100:101]
	v_pk_mul_f32 v[86:87], v[86:87], v[102:103]
	v_pk_mul_f32 v[88:89], v[88:89], v[104:105]
	v_pk_mul_f32 v[90:91], v[90:91], v[106:107]
	v_pk_mul_f32 v[92:93], v[92:93], v[108:109]
	v_pk_mul_f32 v[94:95], v[94:95], v[110:111]
	global_store_dwordx4 v19, v[80:83], s[6:7] offset:0 nt
	global_store_dwordx4 v19, v[84:87], s[6:7] offset:1024 nt
	global_store_dwordx4 v19, v[88:91], s[6:7] offset:2048 nt
	global_store_dwordx4 v19, v[92:95], s[6:7] offset:3072 nt
	s_endpgm
